# GEMM MMA segment heads: duplicated s_waitcnt lgkmcnt(0) removed (36 sites) so each segment opens one issue slot earlier (stacked on v17)
# baseline (speedup 1.0000x reference)
; #define PG8_STAGE(bufoff, gbase, voff) do { _Pragma("unroll") for (int _i = 0; _i < 2; ++_i) \
;         __builtin_amdgcn_global_load_lds((const unsigned*)((const char*)(gbase) + (voff)[_i]), (LAS unsigned*)(lds + (bufoff) + ldsw + _i * 8192), 16, 0, 0); } while (0)
; #define PG8_LDA(dst, b, h) do { _Pragma("unroll") for (int m = 0; m < 4; ++m) _Pragma("unroll") for (int k = 0; k < 2; ++k) dst[m][k] = *(const LAS bf16x8*)(lds + PG8_SA(b, h) + aoff + m * 2048 + k * 1024); } while (0)
; #define PG8_LDB(dst, b, h) do { _Pragma("unroll") for (int n = 0; n < 2; ++n) _Pragma("unroll") for (int k = 0; k < 2; ++k) dst[n][k] = *(const LAS bf16x8*)(lds + PG8_SB(b, h) + boff + n * 2048 + k * 1024); } while (0)
; #define PG8_MMA(ai, bj, At, Bt) do { __builtin_amdgcn_s_setprio(1); _Pragma("unroll") for (int m = 0; m < 4; ++m) _Pragma("unroll") for (int n = 0; n < 2; ++n) _Pragma("unroll") for (int k = 0; k < 2; ++k) \
;         acc[ai][bj][m][n] = __builtin_amdgcn_mfma_f32_16x16x32_bf16(Bt[n][k], At[m][k], acc[ai][bj][m][n], 0, 0, 0); __builtin_amdgcn_s_setprio(0); } while (0)
; #define PG8_WAIT_L(n) asm volatile("s_waitcnt lgkmcnt(" #n ")" ::: "memory")
; template <class Epi>
; DI void gemm_phase(int wv, LAS unsigned char* lds, const GemmD g, const Epi& E) {
;     ...
;         const bool has_next = S.next(ui + 1, nxt);
;         const char* nA = has_next ? (const char*)g.A + (size_t)nxt.pm * 256 * g.lda * 2 : cA; const char* nB = has_next ? (const char*)g.Bt + PG8_BROW(nxt.pn) * (size_t)g.ldb * 2 : cB;
;         for (int t = 0; t < nt; t += 2) {
;             const bool last = (t == nt - 2);
;             const char* a1 = cA + (size_t)(t + 1) * kstep;
;             const char* a2 = last ? nA : cA + (size_t)(t + 2) * kstep; const char* b2 = last ? nB : cB + (size_t)(t + 2) * kstep;
;             const char* a3 = a2 + kstep; const char* b3 = b2 + kstep;
;             PG8_LDB(B0, 0, 0); PG8_SCHED; PG8_LDA(At, 0, 0); PG8_STAGE(PG8_SA(1, 1), a1 + hstepA, voffA);
;             PG8_WAIT_L(8); PG8_BAR; PG8_WAIT_L(0); PG8_MMA(0, 0, At, B0); PG8_BAR; PG8_SCHED;
;             PG8_LDB(B1, 0, 1); PG8_STAGE(PG8_SB(0, 0), b2, voffB);
;             PG8_BAR; PG8_WAIT_L(0); PG8_MMA(0, 1, At, B1); PG8_BAR;
;             PG8_LDA(At, 0, 1); PG8_STAGE(PG8_SA(0, 0), a2, voffA);
;             PG8_BAR; PG8_WAIT_L(0); PG8_MMA(1, 0, At, B0); PG8_BAR; PG8_SCHED;
.LBB0_98:
	s_ashr_i32 s17, s16, 31
	s_lshl_b64 s[20:21], s[16:17], 19
	s_add_u32 s20, s6, s20
	s_addc_u32 s21, s7, s21
	s_and_b64 s[4:5], s[4:5], exec
	s_cselect_b32 s17, s21, s25
	s_cselect_b32 vcc_lo, s20, s24
	s_add_u32 s4, s24, 0x40080
	s_addc_u32 s5, s25, 0
	s_add_u32 vcc_hi, s22, 0x100
	s_addc_u32 s75, s23, 0
	s_mov_b32 s95, -2
	s_add_u32 s22, s4, 0xfffc0080
	s_addc_u32 s23, s5, -1
	s_add_i32 s3, 0, 0x10000
	v_add_u32_e32 v156, s3, v141
	ds_read_b128 v[144:147], v156
	ds_read_b128 v[148:151], v156 offset:1024
	ds_read_b128 v[152:155], v156 offset:2048
	ds_read_b128 v[156:159], v156 offset:3072
	s_cmp_eq_u32 s95, 12
	s_cselect_b32 s23, s17, s23
	s_cselect_b32 s22, vcc_lo, s22
	s_cselect_b32 s25, s19, s75
	s_cselect_b32 s24, s18, vcc_hi
	v_lshl_add_u64 v[164:165], s[4:5], 0, v[136:137]
	s_add_i32 m0, s15, 0xc000
	ds_read_b128 v[160:163], v143
	ds_read_b128 v[176:179], v143 offset:1024
	ds_read_b128 v[180:183], v143 offset:2048
	ds_read_b128 v[184:187], v143 offset:3072
	ds_read_b128 v[188:191], v143 offset:4096
	ds_read_b128 v[192:195], v143 offset:5120
	ds_read_b128 v[196:199], v143 offset:6144
	ds_read_b128 v[200:203], v143 offset:7168
	global_load_lds_dwordx4 v[164:165], off
	v_lshl_add_u64 v[164:165], s[4:5], 0, v[138:139]
	s_add_i32 m0, s15, 0xe000
	s_nop 0
	global_load_lds_dwordx4 v[164:165], off
	s_waitcnt lgkmcnt(8)
	s_barrier
	s_waitcnt lgkmcnt(0)
	v_mfma_f32_16x16x32_bf16 v[126:129], v[144:147], v[160:163], 0
	v_mfma_f32_16x16x32_bf16 v[122:125], v[152:155], v[160:163], 0
	v_mfma_f32_16x16x32_bf16 v[118:121], v[144:147], v[180:183], 0
	v_mfma_f32_16x16x32_bf16 v[114:117], v[152:155], v[180:183], 0
	v_mfma_f32_16x16x32_bf16 v[102:105], v[144:147], v[188:191], 0
	v_mfma_f32_16x16x32_bf16 v[98:101], v[152:155], v[188:191], 0
	v_mfma_f32_16x16x32_bf16 v[86:89], v[144:147], v[196:199], 0
	v_mfma_f32_16x16x32_bf16 v[82:85], v[152:155], v[196:199], 0
	v_mfma_f32_16x16x32_bf16 v[126:129], v[148:151], v[176:179], v[126:129]
	v_mfma_f32_16x16x32_bf16 v[122:125], v[156:159], v[176:179], v[122:125]
	v_mfma_f32_16x16x32_bf16 v[118:121], v[148:151], v[184:187], v[118:121]
	v_mfma_f32_16x16x32_bf16 v[114:117], v[156:159], v[184:187], v[114:117]
	v_mfma_f32_16x16x32_bf16 v[102:105], v[148:151], v[192:195], v[102:105]
	v_mfma_f32_16x16x32_bf16 v[98:101], v[156:159], v[192:195], v[98:101]
	v_mfma_f32_16x16x32_bf16 v[86:89], v[148:151], v[200:203], v[86:89]
	v_mfma_f32_16x16x32_bf16 v[82:85], v[156:159], v[200:203], v[82:85]
	s_barrier
	s_add_i32 s2, 0, 0x14000
	v_add_u32_e32 v164, s2, v141
	s_add_i32 s3, s3, s37
	ds_read_b128 v[204:207], v164
	ds_read_b128 v[208:211], v164 offset:1024
	ds_read_b128 v[212:215], v164 offset:2048
	ds_read_b128 v[216:219], v164 offset:3072
	v_lshl_add_u64 v[164:165], s[24:25], 0, v[0:1]
	s_mov_b32 m0, s3
	v_lshl_add_u64 v[168:169], s[24:25], 0, v[130:131]
	global_load_lds_dwordx4 v[164:165], off
	s_add_i32 m0, s3, 0x2000
	s_nop 0
	global_load_lds_dwordx4 v[168:169], off
	s_barrier
	s_waitcnt lgkmcnt(0)
	v_mfma_f32_16x16x32_bf16 v[110:113], v[204:207], v[160:163], 0
	v_mfma_f32_16x16x32_bf16 v[106:109], v[212:215], v[160:163], 0
	v_mfma_f32_16x16x32_bf16 v[94:97], v[204:207], v[180:183], 0
	v_mfma_f32_16x16x32_bf16 v[90:93], v[212:215], v[180:183], 0
	v_mfma_f32_16x16x32_bf16 v[78:81], v[204:207], v[188:191], 0
	v_mfma_f32_16x16x32_bf16 v[74:77], v[212:215], v[188:191], 0
	v_mfma_f32_16x16x32_bf16 v[70:73], v[204:207], v[196:199], 0
	v_mfma_f32_16x16x32_bf16 v[66:69], v[212:215], v[196:199], 0
	v_mfma_f32_16x16x32_bf16 v[110:113], v[208:211], v[176:179], v[110:113]
	v_mfma_f32_16x16x32_bf16 v[106:109], v[216:219], v[176:179], v[106:109]
	v_mfma_f32_16x16x32_bf16 v[94:97], v[208:211], v[184:187], v[94:97]
	v_mfma_f32_16x16x32_bf16 v[90:93], v[216:219], v[184:187], v[90:93]
	v_mfma_f32_16x16x32_bf16 v[78:81], v[208:211], v[192:195], v[78:81]
	v_mfma_f32_16x16x32_bf16 v[74:77], v[216:219], v[192:195], v[74:77]
	v_mfma_f32_16x16x32_bf16 v[70:73], v[208:211], v[200:203], v[70:73]
	v_mfma_f32_16x16x32_bf16 v[66:69], v[216:219], v[200:203], v[66:69]
	s_mov_b32 m0, s15
	v_lshl_add_u64 v[170:171], s[22:23], 0, v[134:135]
	s_barrier
	ds_read_b128 v[160:163], v143 offset:16384
	ds_read_b128 v[176:179], v143 offset:17408
	ds_read_b128 v[180:183], v143 offset:18432
	ds_read_b128 v[184:187], v143 offset:19456
	ds_read_b128 v[188:191], v143 offset:20480
	ds_read_b128 v[192:195], v143 offset:21504
	ds_read_b128 v[196:199], v143 offset:22528
	ds_read_b128 v[200:203], v143 offset:23552
	global_load_lds_dwordx4 v[170:171], off
	v_lshl_add_u64 v[220:221], s[22:23], 0, v[132:133]
	s_mov_b32 m0, s45
	s_nop 0
	global_load_lds_dwordx4 v[220:221], off
	s_barrier
	s_waitcnt lgkmcnt(0)
	v_mfma_f32_16x16x32_bf16 v[62:65], v[144:147], v[160:163], 0
	v_mfma_f32_16x16x32_bf16 v[58:61], v[152:155], v[160:163], 0
	v_mfma_f32_16x16x32_bf16 v[54:57], v[144:147], v[180:183], 0
	v_mfma_f32_16x16x32_bf16 v[50:53], v[152:155], v[180:183], 0
	v_mfma_f32_16x16x32_bf16 v[38:41], v[144:147], v[188:191], 0
	v_mfma_f32_16x16x32_bf16 v[34:37], v[152:155], v[188:191], 0
	v_mfma_f32_16x16x32_bf16 v[22:25], v[144:147], v[196:199], 0
	v_mfma_f32_16x16x32_bf16 v[18:21], v[152:155], v[196:199], 0
	v_mfma_f32_16x16x32_bf16 v[62:65], v[148:151], v[176:179], v[62:65]
	v_mfma_f32_16x16x32_bf16 v[58:61], v[156:159], v[176:179], v[58:61]
	v_mfma_f32_16x16x32_bf16 v[54:57], v[148:151], v[184:187], v[54:57]
	v_mfma_f32_16x16x32_bf16 v[50:53], v[156:159], v[184:187], v[50:53]
	v_mfma_f32_16x16x32_bf16 v[38:41], v[148:151], v[192:195], v[38:41]
	v_mfma_f32_16x16x32_bf16 v[34:37], v[156:159], v[192:195], v[34:37]
	v_mfma_f32_16x16x32_bf16 v[22:25], v[148:151], v[200:203], v[22:25]
	v_mfma_f32_16x16x32_bf16 v[18:21], v[156:159], v[200:203], v[18:21]
	s_barrier
; #define PG8_STAGE(bufoff, gbase, voff) do { _Pragma("unroll") for (int _i = 0; _i < 2; ++_i) \
;         __builtin_amdgcn_global_load_lds((const unsigned*)((const char*)(gbase) + (voff)[_i]), (LAS unsigned*)(lds + (bufoff) + ldsw + _i * 8192), 16, 0, 0); } while (0)
; #define PG8_LDA(dst, b, h) do { _Pragma("unroll") for (int m = 0; m < 4; ++m) _Pragma("unroll") for (int k = 0; k < 2; ++k) dst[m][k] = *(const LAS bf16x8*)(lds + PG8_SA(b, h) + aoff + m * 2048 + k * 1024); } while (0)
; #define PG8_LDB(dst, b, h) do { _Pragma("unroll") for (int n = 0; n < 2; ++n) _Pragma("unroll") for (int k = 0; k < 2; ++k) dst[n][k] = *(const LAS bf16x8*)(lds + PG8_SB(b, h) + boff + n * 2048 + k * 1024); } while (0)
; #define PG8_MMA(ai, bj, At, Bt) do { __builtin_amdgcn_s_setprio(1); _Pragma("unroll") for (int m = 0; m < 4; ++m) _Pragma("unroll") for (int n = 0; n < 2; ++n) _Pragma("unroll") for (int k = 0; k < 2; ++k) \
;         acc[ai][bj][m][n] = __builtin_amdgcn_mfma_f32_16x16x32_bf16(Bt[n][k], At[m][k], acc[ai][bj][m][n], 0, 0, 0); __builtin_amdgcn_s_setprio(0); } while (0)
; #define PG8_WAIT_V(n) asm volatile("s_waitcnt vmcnt(" #n ")" ::: "memory")
; #define PG8_WAIT_L(n) asm volatile("s_waitcnt lgkmcnt(" #n ")" ::: "memory")
; #define PG8_BAR __builtin_amdgcn_s_barrier()
; #define PG8_SCHED __builtin_amdgcn_sched_barrier(0)
; template <class Epi>
; DI void gemm_phase(int wv, LAS unsigned char* lds, const GemmD g, const Epi& E) {
;     ...
;             PG8_STAGE(PG8_SB(0, 1), b2 + hstepB, voffB);
;             PG8_WAIT_V(6); PG8_BAR; PG8_MMA(1, 1, At, B1); PG8_BAR;
;             PG8_LDB(B0, 1, 0); PG8_SCHED; PG8_LDA(At, 1, 0); PG8_STAGE(PG8_SA(0, 1), a2 + hstepA, voffA);
;             PG8_WAIT_L(8); PG8_BAR; PG8_WAIT_L(0); PG8_MMA(0, 0, At, B0); PG8_BAR; PG8_SCHED;
;             PG8_LDB(B1, 1, 1); PG8_STAGE(PG8_SB(1, 0), b3, voffB);
;             PG8_BAR; PG8_WAIT_L(0); PG8_MMA(0, 1, At, B1); PG8_BAR;
;             PG8_LDA(At, 1, 1); PG8_STAGE(PG8_SA(1, 0), a3, voffA);
	s_add_u32 s24, s24, s36
	s_addc_u32 s25, s25, 0
	s_add_i32 s2, s2, s37
	v_lshl_add_u64 v[222:223], s[24:25], 0, v[0:1]
	s_mov_b32 m0, s2
	v_lshl_add_u64 v[224:225], s[24:25], 0, v[130:131]
	global_load_lds_dwordx4 v[222:223], off
	s_add_i32 m0, s2, 0x2000
	s_nop 0
	global_load_lds_dwordx4 v[224:225], off
	s_waitcnt vmcnt(6)
	s_barrier
	v_mfma_f32_16x16x32_bf16 v[46:49], v[204:207], v[160:163], 0
	v_mfma_f32_16x16x32_bf16 v[42:45], v[212:215], v[160:163], 0
	v_mfma_f32_16x16x32_bf16 v[30:33], v[204:207], v[180:183], 0
	v_mfma_f32_16x16x32_bf16 v[26:29], v[212:215], v[180:183], 0
	v_mfma_f32_16x16x32_bf16 v[14:17], v[204:207], v[188:191], 0
	v_mfma_f32_16x16x32_bf16 v[10:13], v[212:215], v[188:191], 0
	v_mfma_f32_16x16x32_bf16 v[6:9], v[204:207], v[196:199], 0
	v_mfma_f32_16x16x32_bf16 v[2:5], v[212:215], v[196:199], 0
	v_mfma_f32_16x16x32_bf16 v[46:49], v[208:211], v[176:179], v[46:49]
	v_mfma_f32_16x16x32_bf16 v[42:45], v[216:219], v[176:179], v[42:45]
	v_mfma_f32_16x16x32_bf16 v[30:33], v[208:211], v[184:187], v[30:33]
	v_mfma_f32_16x16x32_bf16 v[26:29], v[216:219], v[184:187], v[26:29]
	v_mfma_f32_16x16x32_bf16 v[14:17], v[208:211], v[192:195], v[14:17]
	v_mfma_f32_16x16x32_bf16 v[10:13], v[216:219], v[192:195], v[10:13]
	v_mfma_f32_16x16x32_bf16 v[6:9], v[208:211], v[200:203], v[6:9]
	v_mfma_f32_16x16x32_bf16 v[2:5], v[216:219], v[200:203], v[2:5]
	s_add_i32 s2, 0, 0x18000
	v_add_u32_e32 v156, s2, v141
	s_barrier
	ds_read_b128 v[144:147], v156
	ds_read_b128 v[148:151], v156 offset:1024
	ds_read_b128 v[152:155], v156 offset:2048
	ds_read_b128 v[156:159], v156 offset:3072
	s_add_u32 s22, s22, 0x40000
	s_addc_u32 s23, s23, 0
	s_mov_b32 m0, s82
	v_lshl_add_u64 v[204:205], s[22:23], 0, v[134:135]
	ds_read_b128 v[160:163], v143 offset:32768
	ds_read_b128 v[176:179], v143 offset:33792
	ds_read_b128 v[180:183], v143 offset:34816
	ds_read_b128 v[184:187], v143 offset:35840
	ds_read_b128 v[188:191], v143 offset:36864
	ds_read_b128 v[192:195], v143 offset:37888
	ds_read_b128 v[196:199], v143 offset:38912
	ds_read_b128 v[200:203], v143 offset:39936
	global_load_lds_dwordx4 v[204:205], off
	v_lshl_add_u64 v[204:205], s[22:23], 0, v[132:133]
	s_mov_b32 m0, s83
	s_nop 0
	global_load_lds_dwordx4 v[204:205], off
	s_waitcnt lgkmcnt(8)
	s_barrier
	s_waitcnt lgkmcnt(0)
	v_mfma_f32_16x16x32_bf16 v[126:129], v[144:147], v[160:163], v[126:129]
	v_mfma_f32_16x16x32_bf16 v[122:125], v[152:155], v[160:163], v[122:125]
	v_mfma_f32_16x16x32_bf16 v[118:121], v[144:147], v[180:183], v[118:121]
	v_mfma_f32_16x16x32_bf16 v[114:117], v[152:155], v[180:183], v[114:117]
	v_mfma_f32_16x16x32_bf16 v[102:105], v[144:147], v[188:191], v[102:105]
	v_mfma_f32_16x16x32_bf16 v[98:101], v[152:155], v[188:191], v[98:101]
	v_mfma_f32_16x16x32_bf16 v[86:89], v[144:147], v[196:199], v[86:89]
	v_mfma_f32_16x16x32_bf16 v[82:85], v[152:155], v[196:199], v[82:85]
	v_mfma_f32_16x16x32_bf16 v[126:129], v[148:151], v[176:179], v[126:129]
	v_mfma_f32_16x16x32_bf16 v[122:125], v[156:159], v[176:179], v[122:125]
	v_mfma_f32_16x16x32_bf16 v[118:121], v[148:151], v[184:187], v[118:121]
	v_mfma_f32_16x16x32_bf16 v[114:117], v[156:159], v[184:187], v[114:117]
	v_mfma_f32_16x16x32_bf16 v[102:105], v[148:151], v[192:195], v[102:105]
	v_mfma_f32_16x16x32_bf16 v[98:101], v[156:159], v[192:195], v[98:101]
	v_mfma_f32_16x16x32_bf16 v[86:89], v[148:151], v[200:203], v[86:89]
	v_mfma_f32_16x16x32_bf16 v[82:85], v[156:159], v[200:203], v[82:85]
	s_barrier
	s_add_i32 s3, 0, 0x1c000
	s_add_i32 s2, s2, s37
	v_add_u32_e32 v216, s3, v141
	v_lshl_add_u64 v[164:165], v[164:165], 0, s[58:59]
	s_mov_b32 m0, s2
	ds_read_b128 v[204:207], v216
	ds_read_b128 v[208:211], v216 offset:1024
	ds_read_b128 v[212:215], v216 offset:2048
	ds_read_b128 v[216:219], v216 offset:3072
	global_load_lds_dwordx4 v[164:165], off
	v_lshl_add_u64 v[164:165], v[168:169], 0, s[58:59]
	s_add_i32 m0, s2, 0x2000
	s_nop 0
	global_load_lds_dwordx4 v[164:165], off
	s_barrier
	s_waitcnt lgkmcnt(0)
	v_mfma_f32_16x16x32_bf16 v[110:113], v[204:207], v[160:163], v[110:113]
	v_mfma_f32_16x16x32_bf16 v[106:109], v[212:215], v[160:163], v[106:109]
	v_mfma_f32_16x16x32_bf16 v[94:97], v[204:207], v[180:183], v[94:97]
	v_mfma_f32_16x16x32_bf16 v[90:93], v[212:215], v[180:183], v[90:93]
	v_mfma_f32_16x16x32_bf16 v[78:81], v[204:207], v[188:191], v[78:81]
	v_mfma_f32_16x16x32_bf16 v[74:77], v[212:215], v[188:191], v[74:77]
	v_mfma_f32_16x16x32_bf16 v[70:73], v[204:207], v[196:199], v[70:73]
	v_mfma_f32_16x16x32_bf16 v[66:69], v[212:215], v[196:199], v[66:69]
	v_mfma_f32_16x16x32_bf16 v[110:113], v[208:211], v[176:179], v[110:113]
	v_mfma_f32_16x16x32_bf16 v[106:109], v[216:219], v[176:179], v[106:109]
	v_mfma_f32_16x16x32_bf16 v[94:97], v[208:211], v[184:187], v[94:97]
	v_mfma_f32_16x16x32_bf16 v[90:93], v[216:219], v[184:187], v[90:93]
	v_mfma_f32_16x16x32_bf16 v[78:81], v[208:211], v[192:195], v[78:81]
	v_mfma_f32_16x16x32_bf16 v[74:77], v[216:219], v[192:195], v[74:77]
	v_mfma_f32_16x16x32_bf16 v[70:73], v[208:211], v[200:203], v[70:73]
	v_mfma_f32_16x16x32_bf16 v[66:69], v[216:219], v[200:203], v[66:69]
	s_mov_b32 m0, s84
	v_lshl_add_u64 v[164:165], v[170:171], 0, s[58:59]
	s_barrier
	ds_read_b128 v[160:163], v143 offset:49152
	ds_read_b128 v[176:179], v143 offset:50176
	ds_read_b128 v[180:183], v143 offset:51200
	ds_read_b128 v[184:187], v143 offset:52224
	ds_read_b128 v[188:191], v143 offset:53248
	ds_read_b128 v[192:195], v143 offset:54272
	ds_read_b128 v[196:199], v143 offset:55296
	ds_read_b128 v[200:203], v143 offset:56320
	global_load_lds_dwordx4 v[164:165], off
	v_lshl_add_u64 v[164:165], v[220:221], 0, s[58:59]
	s_mov_b32 m0, s85
	s_nop 0
	global_load_lds_dwordx4 v[164:165], off
	s_barrier
; #define PG8_STAGE(bufoff, gbase, voff) do { _Pragma("unroll") for (int _i = 0; _i < 2; ++_i) \
;         __builtin_amdgcn_global_load_lds((const unsigned*)((const char*)(gbase) + (voff)[_i]), (LAS unsigned*)(lds + (bufoff) + ldsw + _i * 8192), 16, 0, 0); } while (0)
; #define PG8_LDA(dst, b, h) do { _Pragma("unroll") for (int m = 0; m < 4; ++m) _Pragma("unroll") for (int k = 0; k < 2; ++k) dst[m][k] = *(const LAS bf16x8*)(lds + PG8_SA(b, h) + aoff + m * 2048 + k * 1024); } while (0)
; #define PG8_LDB(dst, b, h) do { _Pragma("unroll") for (int n = 0; n < 2; ++n) _Pragma("unroll") for (int k = 0; k < 2; ++k) dst[n][k] = *(const LAS bf16x8*)(lds + PG8_SB(b, h) + boff + n * 2048 + k * 1024); } while (0)
; #define PG8_MMA(ai, bj, At, Bt) do { __builtin_amdgcn_s_setprio(1); _Pragma("unroll") for (int m = 0; m < 4; ++m) _Pragma("unroll") for (int n = 0; n < 2; ++n) _Pragma("unroll") for (int k = 0; k < 2; ++k) \
;         acc[ai][bj][m][n] = __builtin_amdgcn_mfma_f32_16x16x32_bf16(Bt[n][k], At[m][k], acc[ai][bj][m][n], 0, 0, 0); __builtin_amdgcn_s_setprio(0); } while (0)
; #define PG8_WAIT_V(n) asm volatile("s_waitcnt vmcnt(" #n ")" ::: "memory")
; #define PG8_WAIT_L(n) asm volatile("s_waitcnt lgkmcnt(" #n ")" ::: "memory")
; #define PG8_BAR __builtin_amdgcn_s_barrier()
; #define PG8_SCHED __builtin_amdgcn_sched_barrier(0)
; template <class Epi>
; DI void gemm_phase(int wv, LAS unsigned char* lds, const GemmD g, const Epi& E) {
;     ...
;             const bool last = (t == nt - 2);
;             const char* a1 = cA + (size_t)(t + 1) * kstep;
;             const char* a2 = last ? nA : cA + (size_t)(t + 2) * kstep; const char* b2 = last ? nB : cB + (size_t)(t + 2) * kstep;
;             const char* a3 = a2 + kstep; const char* b3 = b2 + kstep;
;             PG8_LDB(B0, 0, 0); PG8_SCHED; PG8_LDA(At, 0, 0); PG8_STAGE(PG8_SA(1, 1), a1 + hstepA, voffA);
;             PG8_WAIT_L(8); PG8_BAR; PG8_WAIT_L(0); PG8_MMA(0, 0, At, B0); PG8_BAR; PG8_SCHED;
;             PG8_LDB(B1, 0, 1); PG8_STAGE(PG8_SB(0, 0), b2, voffB);
;     ...
;             PG8_BAR; PG8_WAIT_L(0); PG8_MMA(1, 0, At, B0); PG8_BAR; PG8_SCHED;
;             PG8_STAGE(PG8_SB(1, 1), b3 + hstepB, voffB);
;             PG8_WAIT_V(6); PG8_BAR; PG8_MMA(1, 1, At, B1); PG8_BAR;
;         }
	s_waitcnt lgkmcnt(0)
	v_mfma_f32_16x16x32_bf16 v[62:65], v[144:147], v[160:163], v[62:65]
	v_mfma_f32_16x16x32_bf16 v[58:61], v[152:155], v[160:163], v[58:61]
	v_mfma_f32_16x16x32_bf16 v[54:57], v[144:147], v[180:183], v[54:57]
	v_mfma_f32_16x16x32_bf16 v[50:53], v[152:155], v[180:183], v[50:53]
	v_mfma_f32_16x16x32_bf16 v[38:41], v[144:147], v[188:191], v[38:41]
	v_mfma_f32_16x16x32_bf16 v[34:37], v[152:155], v[188:191], v[34:37]
	v_mfma_f32_16x16x32_bf16 v[22:25], v[144:147], v[196:199], v[22:25]
	v_mfma_f32_16x16x32_bf16 v[18:21], v[152:155], v[196:199], v[18:21]
	v_mfma_f32_16x16x32_bf16 v[62:65], v[148:151], v[176:179], v[62:65]
	v_mfma_f32_16x16x32_bf16 v[58:61], v[156:159], v[176:179], v[58:61]
	v_mfma_f32_16x16x32_bf16 v[54:57], v[148:151], v[184:187], v[54:57]
	v_mfma_f32_16x16x32_bf16 v[50:53], v[156:159], v[184:187], v[50:53]
	v_mfma_f32_16x16x32_bf16 v[38:41], v[148:151], v[192:195], v[38:41]
	v_mfma_f32_16x16x32_bf16 v[34:37], v[156:159], v[192:195], v[34:37]
	v_mfma_f32_16x16x32_bf16 v[22:25], v[148:151], v[200:203], v[22:25]
	v_mfma_f32_16x16x32_bf16 v[18:21], v[156:159], v[200:203], v[18:21]
	s_barrier
	s_add_i32 s2, s3, s37
	v_lshl_add_u64 v[144:145], v[222:223], 0, s[58:59]
	s_mov_b32 m0, s2
	s_nop 0
	global_load_lds_dwordx4 v[144:145], off
	v_lshl_add_u64 v[144:145], v[224:225], 0, s[58:59]
	s_add_i32 m0, s2, 0x2000
	s_nop 0
	global_load_lds_dwordx4 v[144:145], off
	s_waitcnt vmcnt(6)
	s_barrier
	v_mfma_f32_16x16x32_bf16 v[46:49], v[204:207], v[160:163], v[46:49]
	v_mfma_f32_16x16x32_bf16 v[42:45], v[212:215], v[160:163], v[42:45]
	v_mfma_f32_16x16x32_bf16 v[30:33], v[204:207], v[180:183], v[30:33]
	v_mfma_f32_16x16x32_bf16 v[26:29], v[212:215], v[180:183], v[26:29]
	v_mfma_f32_16x16x32_bf16 v[14:17], v[204:207], v[188:191], v[14:17]
	v_mfma_f32_16x16x32_bf16 v[10:13], v[212:215], v[188:191], v[10:13]
	v_mfma_f32_16x16x32_bf16 v[6:9], v[204:207], v[196:199], v[6:9]
	v_mfma_f32_16x16x32_bf16 v[2:5], v[212:215], v[196:199], v[2:5]
	v_mfma_f32_16x16x32_bf16 v[46:49], v[208:211], v[176:179], v[46:49]
	v_mfma_f32_16x16x32_bf16 v[42:45], v[216:219], v[176:179], v[42:45]
	v_mfma_f32_16x16x32_bf16 v[30:33], v[208:211], v[184:187], v[30:33]
	v_mfma_f32_16x16x32_bf16 v[26:29], v[216:219], v[184:187], v[26:29]
	v_mfma_f32_16x16x32_bf16 v[14:17], v[208:211], v[192:195], v[14:17]
	v_mfma_f32_16x16x32_bf16 v[10:13], v[216:219], v[192:195], v[10:13]
	v_mfma_f32_16x16x32_bf16 v[6:9], v[208:211], v[200:203], v[6:9]
	v_mfma_f32_16x16x32_bf16 v[2:5], v[216:219], v[200:203], v[2:5]
	s_add_i32 s95, s95, 2
	s_add_u32 s4, s4, 0x100
	s_addc_u32 s5, s5, 0
	s_add_u32 vcc_hi, vcc_hi, 0x100
	s_addc_u32 s75, s75, 0
	s_cmp_gt_u32 s95, 13
	s_barrier
	s_cbranch_scc0 .LBB0_99
	s_branch .Lgemm_epi_a
	.p2align 6
.LBB0_99:
	s_add_u32 s22, s4, 0xfffc0080
	s_addc_u32 s23, s5, -1
	s_add_i32 s3, 0, 0x10000
	v_add_u32_e32 v156, s3, v141
	ds_read_b128 v[144:147], v156
	ds_read_b128 v[148:151], v156 offset:1024
	ds_read_b128 v[152:155], v156 offset:2048
	ds_read_b128 v[156:159], v156 offset:3072
	s_cmp_eq_u32 s95, 12
	s_cselect_b32 s23, s17, s23
	s_cselect_b32 s22, vcc_lo, s22
	s_cselect_b32 s25, s19, s75
	s_cselect_b32 s24, s18, vcc_hi
	v_lshl_add_u64 v[164:165], s[4:5], 0, v[136:137]
	s_add_i32 m0, s15, 0xc000
	ds_read_b128 v[160:163], v143
	ds_read_b128 v[176:179], v143 offset:1024
	ds_read_b128 v[180:183], v143 offset:2048
	ds_read_b128 v[184:187], v143 offset:3072
	ds_read_b128 v[188:191], v143 offset:4096
	ds_read_b128 v[192:195], v143 offset:5120
	ds_read_b128 v[196:199], v143 offset:6144
	ds_read_b128 v[200:203], v143 offset:7168
	global_load_lds_dwordx4 v[164:165], off
	v_lshl_add_u64 v[164:165], s[4:5], 0, v[138:139]
	s_add_i32 m0, s15, 0xe000
	s_nop 0
	global_load_lds_dwordx4 v[164:165], off
	s_waitcnt lgkmcnt(8)
	s_barrier
	s_waitcnt lgkmcnt(0)
	v_mfma_f32_16x16x32_bf16 v[126:129], v[144:147], v[160:163], v[126:129]
	v_mfma_f32_16x16x32_bf16 v[122:125], v[152:155], v[160:163], v[122:125]
	v_mfma_f32_16x16x32_bf16 v[118:121], v[144:147], v[180:183], v[118:121]
	v_mfma_f32_16x16x32_bf16 v[114:117], v[152:155], v[180:183], v[114:117]
	v_mfma_f32_16x16x32_bf16 v[102:105], v[144:147], v[188:191], v[102:105]
	v_mfma_f32_16x16x32_bf16 v[98:101], v[152:155], v[188:191], v[98:101]
	v_mfma_f32_16x16x32_bf16 v[86:89], v[144:147], v[196:199], v[86:89]
	v_mfma_f32_16x16x32_bf16 v[82:85], v[152:155], v[196:199], v[82:85]
	v_mfma_f32_16x16x32_bf16 v[126:129], v[148:151], v[176:179], v[126:129]
	v_mfma_f32_16x16x32_bf16 v[122:125], v[156:159], v[176:179], v[122:125]
	v_mfma_f32_16x16x32_bf16 v[118:121], v[148:151], v[184:187], v[118:121]
	v_mfma_f32_16x16x32_bf16 v[114:117], v[156:159], v[184:187], v[114:117]
	v_mfma_f32_16x16x32_bf16 v[102:105], v[148:151], v[192:195], v[102:105]
	v_mfma_f32_16x16x32_bf16 v[98:101], v[156:159], v[192:195], v[98:101]
	v_mfma_f32_16x16x32_bf16 v[86:89], v[148:151], v[200:203], v[86:89]
	v_mfma_f32_16x16x32_bf16 v[82:85], v[156:159], v[200:203], v[82:85]
	s_barrier
	s_add_i32 s2, 0, 0x14000
	v_add_u32_e32 v164, s2, v141
	s_add_i32 s3, s3, s37
	ds_read_b128 v[204:207], v164
	ds_read_b128 v[208:211], v164 offset:1024
	ds_read_b128 v[212:215], v164 offset:2048
	ds_read_b128 v[216:219], v164 offset:3072
	v_lshl_add_u64 v[164:165], s[24:25], 0, v[0:1]
	s_mov_b32 m0, s3
	v_lshl_add_u64 v[168:169], s[24:25], 0, v[130:131]
	global_load_lds_dwordx4 v[164:165], off
	s_add_i32 m0, s3, 0x2000
	s_nop 0
	global_load_lds_dwordx4 v[168:169], off
	s_barrier
; #define PG8_STAGE(bufoff, gbase, voff) do { _Pragma("unroll") for (int _i = 0; _i < 2; ++_i) \
;         __builtin_amdgcn_global_load_lds((const unsigned*)((const char*)(gbase) + (voff)[_i]), (LAS unsigned*)(lds + (bufoff) + ldsw + _i * 8192), 16, 0, 0); } while (0)
; #define PG8_LDA(dst, b, h) do { _Pragma("unroll") for (int m = 0; m < 4; ++m) _Pragma("unroll") for (int k = 0; k < 2; ++k) dst[m][k] = *(const LAS bf16x8*)(lds + PG8_SA(b, h) + aoff + m * 2048 + k * 1024); } while (0)
; #define PG8_LDB(dst, b, h) do { _Pragma("unroll") for (int n = 0; n < 2; ++n) _Pragma("unroll") for (int k = 0; k < 2; ++k) dst[n][k] = *(const LAS bf16x8*)(lds + PG8_SB(b, h) + boff + n * 2048 + k * 1024); } while (0)
; #define PG8_MMA(ai, bj, At, Bt) do { __builtin_amdgcn_s_setprio(1); _Pragma("unroll") for (int m = 0; m < 4; ++m) _Pragma("unroll") for (int n = 0; n < 2; ++n) _Pragma("unroll") for (int k = 0; k < 2; ++k) \
;         acc[ai][bj][m][n] = __builtin_amdgcn_mfma_f32_16x16x32_bf16(Bt[n][k], At[m][k], acc[ai][bj][m][n], 0, 0, 0); __builtin_amdgcn_s_setprio(0); } while (0)
; #define PG8_WAIT_V(n) asm volatile("s_waitcnt vmcnt(" #n ")" ::: "memory")
; #define PG8_WAIT_L(n) asm volatile("s_waitcnt lgkmcnt(" #n ")" ::: "memory")
; #define PG8_BAR __builtin_amdgcn_s_barrier()
; #define PG8_SCHED __builtin_amdgcn_sched_barrier(0)
; template <class Epi>
; DI void gemm_phase(int wv, LAS unsigned char* lds, const GemmD g, const Epi& E) {
;     ...
;             PG8_BAR; PG8_WAIT_L(0); PG8_MMA(0, 1, At, B1); PG8_BAR;
;             PG8_LDA(At, 0, 1); PG8_STAGE(PG8_SA(0, 0), a2, voffA);
;             PG8_BAR; PG8_WAIT_L(0); PG8_MMA(1, 0, At, B0); PG8_BAR; PG8_SCHED;
;             PG8_STAGE(PG8_SB(0, 1), b2 + hstepB, voffB);
;             PG8_WAIT_V(6); PG8_BAR; PG8_MMA(1, 1, At, B1); PG8_BAR;
;             PG8_LDB(B0, 1, 0); PG8_SCHED; PG8_LDA(At, 1, 0); PG8_STAGE(PG8_SA(0, 1), a2 + hstepA, voffA);
;             PG8_WAIT_L(8); PG8_BAR; PG8_WAIT_L(0); PG8_MMA(0, 0, At, B0); PG8_BAR; PG8_SCHED;
	s_waitcnt lgkmcnt(0)
	v_mfma_f32_16x16x32_bf16 v[110:113], v[204:207], v[160:163], v[110:113]
	v_mfma_f32_16x16x32_bf16 v[106:109], v[212:215], v[160:163], v[106:109]
	v_mfma_f32_16x16x32_bf16 v[94:97], v[204:207], v[180:183], v[94:97]
	v_mfma_f32_16x16x32_bf16 v[90:93], v[212:215], v[180:183], v[90:93]
	v_mfma_f32_16x16x32_bf16 v[78:81], v[204:207], v[188:191], v[78:81]
	v_mfma_f32_16x16x32_bf16 v[74:77], v[212:215], v[188:191], v[74:77]
	v_mfma_f32_16x16x32_bf16 v[70:73], v[204:207], v[196:199], v[70:73]
	v_mfma_f32_16x16x32_bf16 v[66:69], v[212:215], v[196:199], v[66:69]
	v_mfma_f32_16x16x32_bf16 v[110:113], v[208:211], v[176:179], v[110:113]
	v_mfma_f32_16x16x32_bf16 v[106:109], v[216:219], v[176:179], v[106:109]
	v_mfma_f32_16x16x32_bf16 v[94:97], v[208:211], v[184:187], v[94:97]
	v_mfma_f32_16x16x32_bf16 v[90:93], v[216:219], v[184:187], v[90:93]
	v_mfma_f32_16x16x32_bf16 v[78:81], v[208:211], v[192:195], v[78:81]
	v_mfma_f32_16x16x32_bf16 v[74:77], v[216:219], v[192:195], v[74:77]
	v_mfma_f32_16x16x32_bf16 v[70:73], v[208:211], v[200:203], v[70:73]
	v_mfma_f32_16x16x32_bf16 v[66:69], v[216:219], v[200:203], v[66:69]
	s_mov_b32 m0, s15
	v_lshl_add_u64 v[170:171], s[22:23], 0, v[134:135]
	s_barrier
	ds_read_b128 v[160:163], v143 offset:16384
	ds_read_b128 v[176:179], v143 offset:17408
	ds_read_b128 v[180:183], v143 offset:18432
	ds_read_b128 v[184:187], v143 offset:19456
	ds_read_b128 v[188:191], v143 offset:20480
	ds_read_b128 v[192:195], v143 offset:21504
	ds_read_b128 v[196:199], v143 offset:22528
	ds_read_b128 v[200:203], v143 offset:23552
	global_load_lds_dwordx4 v[170:171], off
	v_lshl_add_u64 v[220:221], s[22:23], 0, v[132:133]
	s_mov_b32 m0, s45
	s_nop 0
	global_load_lds_dwordx4 v[220:221], off
	s_barrier
	s_waitcnt lgkmcnt(0)
	v_mfma_f32_16x16x32_bf16 v[62:65], v[144:147], v[160:163], v[62:65]
	v_mfma_f32_16x16x32_bf16 v[58:61], v[152:155], v[160:163], v[58:61]
	v_mfma_f32_16x16x32_bf16 v[54:57], v[144:147], v[180:183], v[54:57]
	v_mfma_f32_16x16x32_bf16 v[50:53], v[152:155], v[180:183], v[50:53]
	v_mfma_f32_16x16x32_bf16 v[38:41], v[144:147], v[188:191], v[38:41]
	v_mfma_f32_16x16x32_bf16 v[34:37], v[152:155], v[188:191], v[34:37]
	v_mfma_f32_16x16x32_bf16 v[22:25], v[144:147], v[196:199], v[22:25]
	v_mfma_f32_16x16x32_bf16 v[18:21], v[152:155], v[196:199], v[18:21]
	v_mfma_f32_16x16x32_bf16 v[62:65], v[148:151], v[176:179], v[62:65]
	v_mfma_f32_16x16x32_bf16 v[58:61], v[156:159], v[176:179], v[58:61]
	v_mfma_f32_16x16x32_bf16 v[54:57], v[148:151], v[184:187], v[54:57]
	v_mfma_f32_16x16x32_bf16 v[50:53], v[156:159], v[184:187], v[50:53]
	v_mfma_f32_16x16x32_bf16 v[38:41], v[148:151], v[192:195], v[38:41]
	v_mfma_f32_16x16x32_bf16 v[34:37], v[156:159], v[192:195], v[34:37]
	v_mfma_f32_16x16x32_bf16 v[22:25], v[148:151], v[200:203], v[22:25]
	v_mfma_f32_16x16x32_bf16 v[18:21], v[156:159], v[200:203], v[18:21]
	s_barrier
	s_add_u32 s24, s24, s36
	s_addc_u32 s25, s25, 0
	s_add_i32 s2, s2, s37
	v_lshl_add_u64 v[222:223], s[24:25], 0, v[0:1]
	s_mov_b32 m0, s2
	v_lshl_add_u64 v[224:225], s[24:25], 0, v[130:131]
	global_load_lds_dwordx4 v[222:223], off
	s_add_i32 m0, s2, 0x2000
	s_nop 0
	global_load_lds_dwordx4 v[224:225], off
	s_waitcnt vmcnt(6)
	s_barrier
	v_mfma_f32_16x16x32_bf16 v[46:49], v[204:207], v[160:163], v[46:49]
	v_mfma_f32_16x16x32_bf16 v[42:45], v[212:215], v[160:163], v[42:45]
	v_mfma_f32_16x16x32_bf16 v[30:33], v[204:207], v[180:183], v[30:33]
	v_mfma_f32_16x16x32_bf16 v[26:29], v[212:215], v[180:183], v[26:29]
	v_mfma_f32_16x16x32_bf16 v[14:17], v[204:207], v[188:191], v[14:17]
	v_mfma_f32_16x16x32_bf16 v[10:13], v[212:215], v[188:191], v[10:13]
	v_mfma_f32_16x16x32_bf16 v[6:9], v[204:207], v[196:199], v[6:9]
	v_mfma_f32_16x16x32_bf16 v[2:5], v[212:215], v[196:199], v[2:5]
	v_mfma_f32_16x16x32_bf16 v[46:49], v[208:211], v[176:179], v[46:49]
	v_mfma_f32_16x16x32_bf16 v[42:45], v[216:219], v[176:179], v[42:45]
	v_mfma_f32_16x16x32_bf16 v[30:33], v[208:211], v[184:187], v[30:33]
	v_mfma_f32_16x16x32_bf16 v[26:29], v[216:219], v[184:187], v[26:29]
	v_mfma_f32_16x16x32_bf16 v[14:17], v[208:211], v[192:195], v[14:17]
	v_mfma_f32_16x16x32_bf16 v[10:13], v[216:219], v[192:195], v[10:13]
	v_mfma_f32_16x16x32_bf16 v[6:9], v[208:211], v[200:203], v[6:9]
	v_mfma_f32_16x16x32_bf16 v[2:5], v[216:219], v[200:203], v[2:5]
	s_add_i32 s2, 0, 0x18000
	v_add_u32_e32 v156, s2, v141
	s_barrier
	ds_read_b128 v[144:147], v156
	ds_read_b128 v[148:151], v156 offset:1024
	ds_read_b128 v[152:155], v156 offset:2048
	ds_read_b128 v[156:159], v156 offset:3072
	s_add_u32 s22, s22, 0x40000
	s_addc_u32 s23, s23, 0
	s_mov_b32 m0, s82
	v_lshl_add_u64 v[204:205], s[22:23], 0, v[134:135]
	ds_read_b128 v[160:163], v143 offset:32768
	ds_read_b128 v[176:179], v143 offset:33792
	ds_read_b128 v[180:183], v143 offset:34816
	ds_read_b128 v[184:187], v143 offset:35840
	ds_read_b128 v[188:191], v143 offset:36864
	ds_read_b128 v[192:195], v143 offset:37888
	ds_read_b128 v[196:199], v143 offset:38912
	ds_read_b128 v[200:203], v143 offset:39936
	global_load_lds_dwordx4 v[204:205], off
	v_lshl_add_u64 v[204:205], s[22:23], 0, v[132:133]
	s_mov_b32 m0, s83
	s_nop 0
	global_load_lds_dwordx4 v[204:205], off
	s_waitcnt lgkmcnt(8)
	s_barrier
; #define PG8_STAGE(bufoff, gbase, voff) do { _Pragma("unroll") for (int _i = 0; _i < 2; ++_i) \
;         __builtin_amdgcn_global_load_lds((const unsigned*)((const char*)(gbase) + (voff)[_i]), (LAS unsigned*)(lds + (bufoff) + ldsw + _i * 8192), 16, 0, 0); } while (0)
; #define PG8_LDA(dst, b, h) do { _Pragma("unroll") for (int m = 0; m < 4; ++m) _Pragma("unroll") for (int k = 0; k < 2; ++k) dst[m][k] = *(const LAS bf16x8*)(lds + PG8_SA(b, h) + aoff + m * 2048 + k * 1024); } while (0)
; #define PG8_LDB(dst, b, h) do { _Pragma("unroll") for (int n = 0; n < 2; ++n) _Pragma("unroll") for (int k = 0; k < 2; ++k) dst[n][k] = *(const LAS bf16x8*)(lds + PG8_SB(b, h) + boff + n * 2048 + k * 1024); } while (0)
; #define PG8_MMA(ai, bj, At, Bt) do { __builtin_amdgcn_s_setprio(1); _Pragma("unroll") for (int m = 0; m < 4; ++m) _Pragma("unroll") for (int n = 0; n < 2; ++n) _Pragma("unroll") for (int k = 0; k < 2; ++k) \
;         acc[ai][bj][m][n] = __builtin_amdgcn_mfma_f32_16x16x32_bf16(Bt[n][k], At[m][k], acc[ai][bj][m][n], 0, 0, 0); __builtin_amdgcn_s_setprio(0); } while (0)
; #define PG8_WAIT_V(n) asm volatile("s_waitcnt vmcnt(" #n ")" ::: "memory")
; #define PG8_WAIT_L(n) asm volatile("s_waitcnt lgkmcnt(" #n ")" ::: "memory")
; #define PG8_BAR __builtin_amdgcn_s_barrier()
; #define PG8_SCHED __builtin_amdgcn_sched_barrier(0)
; template <class Epi>
; DI void gemm_phase(int wv, LAS unsigned char* lds, const GemmD g, const Epi& E) {
;     ...
;             PG8_WAIT_L(8); PG8_BAR; PG8_WAIT_L(0); PG8_MMA(0, 0, At, B0); PG8_BAR; PG8_SCHED;
;             PG8_LDB(B1, 1, 1); PG8_STAGE(PG8_SB(1, 0), b3, voffB);
;             PG8_BAR; PG8_WAIT_L(0); PG8_MMA(0, 1, At, B1); PG8_BAR;
;             PG8_LDA(At, 1, 1); PG8_STAGE(PG8_SA(1, 0), a3, voffA);
;             PG8_BAR; PG8_WAIT_L(0); PG8_MMA(1, 0, At, B0); PG8_BAR; PG8_SCHED;
;             PG8_STAGE(PG8_SB(1, 1), b3 + hstepB, voffB);
;             PG8_WAIT_V(6); PG8_BAR; PG8_MMA(1, 1, At, B1); PG8_BAR;
;         }
	s_waitcnt lgkmcnt(0)
	v_mfma_f32_16x16x32_bf16 v[126:129], v[144:147], v[160:163], v[126:129]
	v_mfma_f32_16x16x32_bf16 v[122:125], v[152:155], v[160:163], v[122:125]
	v_mfma_f32_16x16x32_bf16 v[118:121], v[144:147], v[180:183], v[118:121]
	v_mfma_f32_16x16x32_bf16 v[114:117], v[152:155], v[180:183], v[114:117]
	v_mfma_f32_16x16x32_bf16 v[102:105], v[144:147], v[188:191], v[102:105]
	v_mfma_f32_16x16x32_bf16 v[98:101], v[152:155], v[188:191], v[98:101]
	v_mfma_f32_16x16x32_bf16 v[86:89], v[144:147], v[196:199], v[86:89]
	v_mfma_f32_16x16x32_bf16 v[82:85], v[152:155], v[196:199], v[82:85]
	v_mfma_f32_16x16x32_bf16 v[126:129], v[148:151], v[176:179], v[126:129]
	v_mfma_f32_16x16x32_bf16 v[122:125], v[156:159], v[176:179], v[122:125]
	v_mfma_f32_16x16x32_bf16 v[118:121], v[148:151], v[184:187], v[118:121]
	v_mfma_f32_16x16x32_bf16 v[114:117], v[156:159], v[184:187], v[114:117]
	v_mfma_f32_16x16x32_bf16 v[102:105], v[148:151], v[192:195], v[102:105]
	v_mfma_f32_16x16x32_bf16 v[98:101], v[156:159], v[192:195], v[98:101]
	v_mfma_f32_16x16x32_bf16 v[86:89], v[148:151], v[200:203], v[86:89]
	v_mfma_f32_16x16x32_bf16 v[82:85], v[156:159], v[200:203], v[82:85]
	s_barrier
	s_add_i32 s3, 0, 0x1c000
	s_add_i32 s2, s2, s37
	v_add_u32_e32 v216, s3, v141
	v_lshl_add_u64 v[164:165], v[164:165], 0, s[58:59]
	s_mov_b32 m0, s2
	ds_read_b128 v[204:207], v216
	ds_read_b128 v[208:211], v216 offset:1024
	ds_read_b128 v[212:215], v216 offset:2048
	ds_read_b128 v[216:219], v216 offset:3072
	global_load_lds_dwordx4 v[164:165], off
	v_lshl_add_u64 v[164:165], v[168:169], 0, s[58:59]
	s_add_i32 m0, s2, 0x2000
	s_nop 0
	global_load_lds_dwordx4 v[164:165], off
	s_barrier
	s_waitcnt lgkmcnt(0)
	v_mfma_f32_16x16x32_bf16 v[110:113], v[204:207], v[160:163], v[110:113]
	v_mfma_f32_16x16x32_bf16 v[106:109], v[212:215], v[160:163], v[106:109]
	v_mfma_f32_16x16x32_bf16 v[94:97], v[204:207], v[180:183], v[94:97]
	v_mfma_f32_16x16x32_bf16 v[90:93], v[212:215], v[180:183], v[90:93]
	v_mfma_f32_16x16x32_bf16 v[78:81], v[204:207], v[188:191], v[78:81]
	v_mfma_f32_16x16x32_bf16 v[74:77], v[212:215], v[188:191], v[74:77]
	v_mfma_f32_16x16x32_bf16 v[70:73], v[204:207], v[196:199], v[70:73]
	v_mfma_f32_16x16x32_bf16 v[66:69], v[212:215], v[196:199], v[66:69]
	v_mfma_f32_16x16x32_bf16 v[110:113], v[208:211], v[176:179], v[110:113]
	v_mfma_f32_16x16x32_bf16 v[106:109], v[216:219], v[176:179], v[106:109]
	v_mfma_f32_16x16x32_bf16 v[94:97], v[208:211], v[184:187], v[94:97]
	v_mfma_f32_16x16x32_bf16 v[90:93], v[216:219], v[184:187], v[90:93]
	v_mfma_f32_16x16x32_bf16 v[78:81], v[208:211], v[192:195], v[78:81]
	v_mfma_f32_16x16x32_bf16 v[74:77], v[216:219], v[192:195], v[74:77]
	v_mfma_f32_16x16x32_bf16 v[70:73], v[208:211], v[200:203], v[70:73]
	v_mfma_f32_16x16x32_bf16 v[66:69], v[216:219], v[200:203], v[66:69]
	s_mov_b32 m0, s84
	v_lshl_add_u64 v[164:165], v[170:171], 0, s[58:59]
	s_barrier
	ds_read_b128 v[160:163], v143 offset:49152
	ds_read_b128 v[176:179], v143 offset:50176
	ds_read_b128 v[180:183], v143 offset:51200
	ds_read_b128 v[184:187], v143 offset:52224
	ds_read_b128 v[188:191], v143 offset:53248
	ds_read_b128 v[192:195], v143 offset:54272
	ds_read_b128 v[196:199], v143 offset:55296
	ds_read_b128 v[200:203], v143 offset:56320
	global_load_lds_dwordx4 v[164:165], off
	v_lshl_add_u64 v[164:165], v[220:221], 0, s[58:59]
	s_mov_b32 m0, s85
	s_nop 0
	global_load_lds_dwordx4 v[164:165], off
	s_barrier
	s_waitcnt lgkmcnt(0)
	v_mfma_f32_16x16x32_bf16 v[62:65], v[144:147], v[160:163], v[62:65]
	v_mfma_f32_16x16x32_bf16 v[58:61], v[152:155], v[160:163], v[58:61]
	v_mfma_f32_16x16x32_bf16 v[54:57], v[144:147], v[180:183], v[54:57]
	v_mfma_f32_16x16x32_bf16 v[50:53], v[152:155], v[180:183], v[50:53]
	v_mfma_f32_16x16x32_bf16 v[38:41], v[144:147], v[188:191], v[38:41]
	v_mfma_f32_16x16x32_bf16 v[34:37], v[152:155], v[188:191], v[34:37]
	v_mfma_f32_16x16x32_bf16 v[22:25], v[144:147], v[196:199], v[22:25]
	v_mfma_f32_16x16x32_bf16 v[18:21], v[152:155], v[196:199], v[18:21]
	v_mfma_f32_16x16x32_bf16 v[62:65], v[148:151], v[176:179], v[62:65]
	v_mfma_f32_16x16x32_bf16 v[58:61], v[156:159], v[176:179], v[58:61]
	v_mfma_f32_16x16x32_bf16 v[54:57], v[148:151], v[184:187], v[54:57]
	v_mfma_f32_16x16x32_bf16 v[50:53], v[156:159], v[184:187], v[50:53]
	v_mfma_f32_16x16x32_bf16 v[38:41], v[148:151], v[192:195], v[38:41]
	v_mfma_f32_16x16x32_bf16 v[34:37], v[156:159], v[192:195], v[34:37]
	v_mfma_f32_16x16x32_bf16 v[22:25], v[148:151], v[200:203], v[22:25]
	v_mfma_f32_16x16x32_bf16 v[18:21], v[156:159], v[200:203], v[18:21]
	s_barrier
	s_add_i32 s2, s3, s37
	v_lshl_add_u64 v[144:145], v[222:223], 0, s[58:59]
	s_mov_b32 m0, s2
	s_nop 0
	global_load_lds_dwordx4 v[144:145], off
	v_lshl_add_u64 v[144:145], v[224:225], 0, s[58:59]
	s_add_i32 m0, s2, 0x2000
	s_nop 0
	global_load_lds_dwordx4 v[144:145], off
	s_waitcnt vmcnt(6)
	s_barrier
	v_mfma_f32_16x16x32_bf16 v[46:49], v[204:207], v[160:163], v[46:49]
	v_mfma_f32_16x16x32_bf16 v[42:45], v[212:215], v[160:163], v[42:45]
	v_mfma_f32_16x16x32_bf16 v[30:33], v[204:207], v[180:183], v[30:33]
	v_mfma_f32_16x16x32_bf16 v[26:29], v[212:215], v[180:183], v[26:29]
	v_mfma_f32_16x16x32_bf16 v[14:17], v[204:207], v[188:191], v[14:17]
	v_mfma_f32_16x16x32_bf16 v[10:13], v[212:215], v[188:191], v[10:13]
	v_mfma_f32_16x16x32_bf16 v[6:9], v[204:207], v[196:199], v[6:9]
	v_mfma_f32_16x16x32_bf16 v[2:5], v[212:215], v[196:199], v[2:5]
	v_mfma_f32_16x16x32_bf16 v[46:49], v[208:211], v[176:179], v[46:49]
	v_mfma_f32_16x16x32_bf16 v[42:45], v[216:219], v[176:179], v[42:45]
	v_mfma_f32_16x16x32_bf16 v[30:33], v[208:211], v[184:187], v[30:33]
	v_mfma_f32_16x16x32_bf16 v[26:29], v[216:219], v[184:187], v[26:29]
	v_mfma_f32_16x16x32_bf16 v[14:17], v[208:211], v[192:195], v[14:17]
	v_mfma_f32_16x16x32_bf16 v[10:13], v[216:219], v[192:195], v[10:13]
	v_mfma_f32_16x16x32_bf16 v[6:9], v[208:211], v[200:203], v[6:9]
	v_mfma_f32_16x16x32_bf16 v[2:5], v[216:219], v[200:203], v[2:5]
	s_add_i32 s95, s95, 2
	s_add_u32 s4, s4, 0x100
	s_addc_u32 s5, s5, 0
	s_add_u32 vcc_hi, vcc_hi, 0x100
	s_addc_u32 s75, s75, 0
	s_cmp_gt_u32 s95, 13
	s_barrier
	s_cbranch_scc0 .LBB0_99

; #define PG8_STAGE(bufoff, gbase, voff) do { _Pragma("unroll") for (int _i = 0; _i < 2; ++_i) \
;         __builtin_amdgcn_global_load_lds((const unsigned*)((const char*)(gbase) + (voff)[_i]), (LAS unsigned*)(lds + (bufoff) + ldsw + _i * 8192), 16, 0, 0); } while (0)
; #define PG8_LDA(dst, b, h) do { _Pragma("unroll") for (int m = 0; m < 4; ++m) _Pragma("unroll") for (int k = 0; k < 2; ++k) dst[m][k] = *(const LAS bf16x8*)(lds + PG8_SA(b, h) + aoff + m * 2048 + k * 1024); } while (0)
; #define PG8_LDB(dst, b, h) do { _Pragma("unroll") for (int n = 0; n < 2; ++n) _Pragma("unroll") for (int k = 0; k < 2; ++k) dst[n][k] = *(const LAS bf16x8*)(lds + PG8_SB(b, h) + boff + n * 2048 + k * 1024); } while (0)
; #define PG8_MMA(ai, bj, At, Bt) do { __builtin_amdgcn_s_setprio(1); _Pragma("unroll") for (int m = 0; m < 4; ++m) _Pragma("unroll") for (int n = 0; n < 2; ++n) _Pragma("unroll") for (int k = 0; k < 2; ++k) \
;         acc[ai][bj][m][n] = __builtin_amdgcn_mfma_f32_16x16x32_bf16(Bt[n][k], At[m][k], acc[ai][bj][m][n], 0, 0, 0); __builtin_amdgcn_s_setprio(0); } while (0)
; #define PG8_WAIT_L(n) asm volatile("s_waitcnt lgkmcnt(" #n ")" ::: "memory")
; template <class Epi>
; DI void gemm_phase(int wv, LAS unsigned char* lds, const GemmD g, const Epi& E) {
;     ...
;         const bool has_next = S.next(ui + 1, nxt);
;         const char* nA = has_next ? (const char*)g.A + (size_t)nxt.pm * 256 * g.lda * 2 : cA; const char* nB = has_next ? (const char*)g.Bt + PG8_BROW(nxt.pn) * (size_t)g.ldb * 2 : cB;
;         for (int t = 0; t < nt; t += 2) {
;             const bool last = (t == nt - 2);
;             const char* a1 = cA + (size_t)(t + 1) * kstep;
;             const char* a2 = last ? nA : cA + (size_t)(t + 2) * kstep; const char* b2 = last ? nB : cB + (size_t)(t + 2) * kstep;
;             const char* a3 = a2 + kstep; const char* b3 = b2 + kstep;
;             PG8_LDB(B0, 0, 0); PG8_SCHED; PG8_LDA(At, 0, 0); PG8_STAGE(PG8_SA(1, 1), a1 + hstepA, voffA);
;             PG8_WAIT_L(8); PG8_BAR; PG8_WAIT_L(0); PG8_MMA(0, 0, At, B0); PG8_BAR; PG8_SCHED;
;             PG8_LDB(B1, 0, 1); PG8_STAGE(PG8_SB(0, 0), b2, voffB);
;             PG8_BAR; PG8_WAIT_L(0); PG8_MMA(0, 1, At, B1); PG8_BAR;
;             PG8_LDA(At, 0, 1); PG8_STAGE(PG8_SA(0, 0), a2, voffA);
;             PG8_BAR; PG8_WAIT_L(0); PG8_MMA(1, 0, At, B0); PG8_BAR; PG8_SCHED;
.LBB0_489:
	s_ashr_i32 s7, s6, 31
	v_cmp_lt_i64_e32 vcc, s[8:9], v[228:229]
	s_lshl_b64 s[8:9], s[6:7], 19
	s_add_u32 s8, s76, s8
	s_addc_u32 s9, s78, s9
	s_and_b64 s[16:17], vcc, exec
	s_cselect_b32 s7, s9, s27
	s_cselect_b32 s13, s8, s26
	s_lshl_b32 s16, s86, 8
	s_ashr_i32 s17, s16, 31
	s_lshl_b64 s[16:17], s[16:17], 11
	s_add_u32 s22, s39, s16
	s_addc_u32 s23, s40, s17
	s_and_b64 s[16:17], vcc, exec
	s_cselect_b32 s16, s23, s29
	s_cselect_b32 s17, s22, s28
	s_add_u32 s26, s26, 0x40080
	s_addc_u32 s27, s27, 0
	s_add_u32 s36, s28, 0x100
	s_addc_u32 s38, s29, 0
	s_mov_b32 s41, -2
	s_add_u32 s2, s26, 0xfffc0080
	s_addc_u32 s3, s27, -1
	s_add_i32 s18, 0, 0x10000
	v_add_u32_e32 v140, s18, v144
	ds_read_b128 v[148:151], v140
	ds_read_b128 v[152:155], v140 offset:1024
	ds_read_b128 v[156:159], v140 offset:2048
	ds_read_b128 v[160:163], v140 offset:3072
	s_cmp_eq_u32 s41, 12
	s_cselect_b32 s31, s7, s3
	s_cselect_b32 s30, s13, s2
	s_cselect_b32 s29, s16, s38
	s_cselect_b32 s28, s17, s36
	v_lshl_add_u64 v[140:141], s[26:27], 0, v[136:137]
	s_add_i32 m0, s25, 0xc000
	ds_read_b128 v[168:171], v146
	ds_read_b128 v[176:179], v146 offset:1024
	ds_read_b128 v[180:183], v146 offset:2048
	ds_read_b128 v[184:187], v146 offset:3072
	ds_read_b128 v[188:191], v146 offset:4096
	ds_read_b128 v[192:195], v146 offset:5120
	ds_read_b128 v[196:199], v146 offset:6144
	ds_read_b128 v[200:203], v146 offset:7168
	global_load_lds_dwordx4 v[140:141], off
	v_lshl_add_u64 v[140:141], s[26:27], 0, v[138:139]
	s_add_i32 m0, s25, 0xe000
	s_nop 0
	global_load_lds_dwordx4 v[140:141], off
	s_waitcnt lgkmcnt(8)
	s_barrier
	s_waitcnt lgkmcnt(0)
	v_mfma_f32_16x16x32_bf16 v[126:129], v[148:151], v[168:171], 0
	v_mfma_f32_16x16x32_bf16 v[122:125], v[156:159], v[168:171], 0
	v_mfma_f32_16x16x32_bf16 v[110:113], v[148:151], v[180:183], 0
	v_mfma_f32_16x16x32_bf16 v[106:109], v[156:159], v[180:183], 0
	v_mfma_f32_16x16x32_bf16 v[94:97], v[148:151], v[188:191], 0
	v_mfma_f32_16x16x32_bf16 v[90:93], v[156:159], v[188:191], 0
	v_mfma_f32_16x16x32_bf16 v[78:81], v[148:151], v[196:199], 0
	v_mfma_f32_16x16x32_bf16 v[74:77], v[156:159], v[196:199], 0
	v_mfma_f32_16x16x32_bf16 v[126:129], v[152:155], v[176:179], v[126:129]
	v_mfma_f32_16x16x32_bf16 v[122:125], v[160:163], v[176:179], v[122:125]
	v_mfma_f32_16x16x32_bf16 v[110:113], v[152:155], v[184:187], v[110:113]
	v_mfma_f32_16x16x32_bf16 v[106:109], v[160:163], v[184:187], v[106:109]
	v_mfma_f32_16x16x32_bf16 v[94:97], v[152:155], v[192:195], v[94:97]
	v_mfma_f32_16x16x32_bf16 v[90:93], v[160:163], v[192:195], v[90:93]
	v_mfma_f32_16x16x32_bf16 v[78:81], v[152:155], v[200:203], v[78:81]
	v_mfma_f32_16x16x32_bf16 v[74:77], v[160:163], v[200:203], v[74:77]
	s_barrier
	s_add_i32 s2, 0, 0x14000
	v_add_u32_e32 v140, s2, v144
	s_add_i32 s3, s18, s79
	ds_read_b128 v[204:207], v140
	ds_read_b128 v[208:211], v140 offset:1024
	ds_read_b128 v[212:215], v140 offset:2048
	ds_read_b128 v[216:219], v140 offset:3072
	v_lshl_add_u64 v[140:141], s[28:29], 0, v[0:1]
	s_mov_b32 m0, s3
	v_lshl_add_u64 v[164:165], s[28:29], 0, v[134:135]
	global_load_lds_dwordx4 v[140:141], off
	s_add_i32 m0, s3, 0x2000
	s_nop 0
	global_load_lds_dwordx4 v[164:165], off
	s_barrier
	s_waitcnt lgkmcnt(0)
	v_mfma_f32_16x16x32_bf16 v[118:121], v[204:207], v[168:171], 0
	v_mfma_f32_16x16x32_bf16 v[114:117], v[212:215], v[168:171], 0
	v_mfma_f32_16x16x32_bf16 v[102:105], v[204:207], v[180:183], 0
	v_mfma_f32_16x16x32_bf16 v[98:101], v[212:215], v[180:183], 0
	v_mfma_f32_16x16x32_bf16 v[86:89], v[204:207], v[188:191], 0
	v_mfma_f32_16x16x32_bf16 v[82:85], v[212:215], v[188:191], 0
	v_mfma_f32_16x16x32_bf16 v[70:73], v[204:207], v[196:199], 0
	v_mfma_f32_16x16x32_bf16 v[66:69], v[212:215], v[196:199], 0
	v_mfma_f32_16x16x32_bf16 v[118:121], v[208:211], v[176:179], v[118:121]
	v_mfma_f32_16x16x32_bf16 v[114:117], v[216:219], v[176:179], v[114:117]
	v_mfma_f32_16x16x32_bf16 v[102:105], v[208:211], v[184:187], v[102:105]
	v_mfma_f32_16x16x32_bf16 v[98:101], v[216:219], v[184:187], v[98:101]
	v_mfma_f32_16x16x32_bf16 v[86:89], v[208:211], v[192:195], v[86:89]
	v_mfma_f32_16x16x32_bf16 v[82:85], v[216:219], v[192:195], v[82:85]
	v_mfma_f32_16x16x32_bf16 v[70:73], v[208:211], v[200:203], v[70:73]
	v_mfma_f32_16x16x32_bf16 v[66:69], v[216:219], v[200:203], v[66:69]
	s_mov_b32 m0, s25
	v_lshl_add_u64 v[220:221], s[30:31], 0, v[130:131]
	s_barrier
	ds_read_b128 v[168:171], v146 offset:16384
	ds_read_b128 v[176:179], v146 offset:17408
	ds_read_b128 v[180:183], v146 offset:18432
	ds_read_b128 v[184:187], v146 offset:19456
	ds_read_b128 v[188:191], v146 offset:20480
	ds_read_b128 v[192:195], v146 offset:21504
	ds_read_b128 v[196:199], v146 offset:22528
	ds_read_b128 v[200:203], v146 offset:23552
	global_load_lds_dwordx4 v[220:221], off
	v_lshl_add_u64 v[222:223], s[30:31], 0, v[132:133]
	s_mov_b32 m0, s80
	s_nop 0
	global_load_lds_dwordx4 v[222:223], off
	s_barrier
	s_waitcnt lgkmcnt(0)
	v_mfma_f32_16x16x32_bf16 v[62:65], v[148:151], v[168:171], 0
	v_mfma_f32_16x16x32_bf16 v[58:61], v[156:159], v[168:171], 0
	v_mfma_f32_16x16x32_bf16 v[46:49], v[148:151], v[180:183], 0
	v_mfma_f32_16x16x32_bf16 v[42:45], v[156:159], v[180:183], 0
	v_mfma_f32_16x16x32_bf16 v[30:33], v[148:151], v[188:191], 0
	v_mfma_f32_16x16x32_bf16 v[26:29], v[156:159], v[188:191], 0
	v_mfma_f32_16x16x32_bf16 v[14:17], v[148:151], v[196:199], 0
	v_mfma_f32_16x16x32_bf16 v[10:13], v[156:159], v[196:199], 0
	v_mfma_f32_16x16x32_bf16 v[62:65], v[152:155], v[176:179], v[62:65]
	v_mfma_f32_16x16x32_bf16 v[58:61], v[160:163], v[176:179], v[58:61]
	v_mfma_f32_16x16x32_bf16 v[46:49], v[152:155], v[184:187], v[46:49]
	v_mfma_f32_16x16x32_bf16 v[42:45], v[160:163], v[184:187], v[42:45]
	v_mfma_f32_16x16x32_bf16 v[30:33], v[152:155], v[192:195], v[30:33]
	v_mfma_f32_16x16x32_bf16 v[26:29], v[160:163], v[192:195], v[26:29]
	v_mfma_f32_16x16x32_bf16 v[14:17], v[152:155], v[200:203], v[14:17]
	v_mfma_f32_16x16x32_bf16 v[10:13], v[160:163], v[200:203], v[10:13]
	s_barrier
; #define PG8_STAGE(bufoff, gbase, voff) do { _Pragma("unroll") for (int _i = 0; _i < 2; ++_i) \
;         __builtin_amdgcn_global_load_lds((const unsigned*)((const char*)(gbase) + (voff)[_i]), (LAS unsigned*)(lds + (bufoff) + ldsw + _i * 8192), 16, 0, 0); } while (0)
; #define PG8_LDA(dst, b, h) do { _Pragma("unroll") for (int m = 0; m < 4; ++m) _Pragma("unroll") for (int k = 0; k < 2; ++k) dst[m][k] = *(const LAS bf16x8*)(lds + PG8_SA(b, h) + aoff + m * 2048 + k * 1024); } while (0)
; #define PG8_LDB(dst, b, h) do { _Pragma("unroll") for (int n = 0; n < 2; ++n) _Pragma("unroll") for (int k = 0; k < 2; ++k) dst[n][k] = *(const LAS bf16x8*)(lds + PG8_SB(b, h) + boff + n * 2048 + k * 1024); } while (0)
; #define PG8_MMA(ai, bj, At, Bt) do { __builtin_amdgcn_s_setprio(1); _Pragma("unroll") for (int m = 0; m < 4; ++m) _Pragma("unroll") for (int n = 0; n < 2; ++n) _Pragma("unroll") for (int k = 0; k < 2; ++k) \
;         acc[ai][bj][m][n] = __builtin_amdgcn_mfma_f32_16x16x32_bf16(Bt[n][k], At[m][k], acc[ai][bj][m][n], 0, 0, 0); __builtin_amdgcn_s_setprio(0); } while (0)
; #define PG8_WAIT_V(n) asm volatile("s_waitcnt vmcnt(" #n ")" ::: "memory")
; #define PG8_WAIT_L(n) asm volatile("s_waitcnt lgkmcnt(" #n ")" ::: "memory")
; #define PG8_BAR __builtin_amdgcn_s_barrier()
; #define PG8_SCHED __builtin_amdgcn_sched_barrier(0)
; template <class Epi>
; DI void gemm_phase(int wv, LAS unsigned char* lds, const GemmD g, const Epi& E) {
;     ...
;             PG8_STAGE(PG8_SB(0, 1), b2 + hstepB, voffB);
;             PG8_WAIT_V(6); PG8_BAR; PG8_MMA(1, 1, At, B1); PG8_BAR;
;             PG8_LDB(B0, 1, 0); PG8_SCHED; PG8_LDA(At, 1, 0); PG8_STAGE(PG8_SA(0, 1), a2 + hstepA, voffA);
;             PG8_WAIT_L(8); PG8_BAR; PG8_WAIT_L(0); PG8_MMA(0, 0, At, B0); PG8_BAR; PG8_SCHED;
;             PG8_LDB(B1, 1, 1); PG8_STAGE(PG8_SB(1, 0), b3, voffB);
;             PG8_BAR; PG8_WAIT_L(0); PG8_MMA(0, 1, At, B1); PG8_BAR;
;             PG8_LDA(At, 1, 1); PG8_STAGE(PG8_SA(1, 0), a3, voffA);
	s_add_u32 s18, s28, 0x40000
	s_addc_u32 s19, s29, 0
	s_add_i32 s2, s2, s79
	v_lshl_add_u64 v[148:149], s[18:19], 0, v[0:1]
	s_mov_b32 m0, s2
	s_nop 0
	global_load_lds_dwordx4 v[148:149], off
	v_lshl_add_u64 v[148:149], s[18:19], 0, v[134:135]
	s_add_i32 m0, s2, 0x2000
	s_nop 0
	global_load_lds_dwordx4 v[148:149], off
	s_waitcnt vmcnt(6)
	s_barrier
	v_mfma_f32_16x16x32_bf16 v[54:57], v[204:207], v[168:171], 0
	v_mfma_f32_16x16x32_bf16 v[50:53], v[212:215], v[168:171], 0
	v_mfma_f32_16x16x32_bf16 v[38:41], v[204:207], v[180:183], 0
	v_mfma_f32_16x16x32_bf16 v[34:37], v[212:215], v[180:183], 0
	v_mfma_f32_16x16x32_bf16 v[22:25], v[204:207], v[188:191], 0
	v_mfma_f32_16x16x32_bf16 v[18:21], v[212:215], v[188:191], 0
	v_mfma_f32_16x16x32_bf16 v[6:9], v[204:207], v[196:199], 0
	v_mfma_f32_16x16x32_bf16 v[2:5], v[212:215], v[196:199], 0
	v_mfma_f32_16x16x32_bf16 v[54:57], v[208:211], v[176:179], v[54:57]
	v_mfma_f32_16x16x32_bf16 v[50:53], v[216:219], v[176:179], v[50:53]
	v_mfma_f32_16x16x32_bf16 v[38:41], v[208:211], v[184:187], v[38:41]
	v_mfma_f32_16x16x32_bf16 v[34:37], v[216:219], v[184:187], v[34:37]
	v_mfma_f32_16x16x32_bf16 v[22:25], v[208:211], v[192:195], v[22:25]
	v_mfma_f32_16x16x32_bf16 v[18:21], v[216:219], v[192:195], v[18:21]
	v_mfma_f32_16x16x32_bf16 v[6:9], v[208:211], v[200:203], v[6:9]
	v_mfma_f32_16x16x32_bf16 v[2:5], v[216:219], v[200:203], v[2:5]
	s_add_i32 s2, 0, 0x18000
	v_add_u32_e32 v147, s2, v144
	s_barrier
	ds_read_b128 v[148:151], v147
	ds_read_b128 v[152:155], v147 offset:1024
	ds_read_b128 v[156:159], v147 offset:2048
	ds_read_b128 v[160:163], v147 offset:3072
	s_add_u32 s18, s30, 0x40000
	s_addc_u32 s19, s31, 0
	s_mov_b32 m0, s81
	v_lshl_add_u64 v[204:205], s[18:19], 0, v[130:131]
	ds_read_b128 v[168:171], v146 offset:32768
	ds_read_b128 v[176:179], v146 offset:33792
	ds_read_b128 v[180:183], v146 offset:34816
	ds_read_b128 v[184:187], v146 offset:35840
	ds_read_b128 v[188:191], v146 offset:36864
	ds_read_b128 v[192:195], v146 offset:37888
	ds_read_b128 v[196:199], v146 offset:38912
	ds_read_b128 v[200:203], v146 offset:39936
	global_load_lds_dwordx4 v[204:205], off
	v_lshl_add_u64 v[204:205], s[18:19], 0, v[132:133]
	s_mov_b32 m0, s82
	s_nop 0
	global_load_lds_dwordx4 v[204:205], off
	s_waitcnt lgkmcnt(8)
	s_barrier
	s_waitcnt lgkmcnt(0)
	v_mfma_f32_16x16x32_bf16 v[126:129], v[148:151], v[168:171], v[126:129]
	v_mfma_f32_16x16x32_bf16 v[122:125], v[156:159], v[168:171], v[122:125]
	v_mfma_f32_16x16x32_bf16 v[110:113], v[148:151], v[180:183], v[110:113]
	v_mfma_f32_16x16x32_bf16 v[106:109], v[156:159], v[180:183], v[106:109]
	v_mfma_f32_16x16x32_bf16 v[94:97], v[148:151], v[188:191], v[94:97]
	v_mfma_f32_16x16x32_bf16 v[90:93], v[156:159], v[188:191], v[90:93]
	v_mfma_f32_16x16x32_bf16 v[78:81], v[148:151], v[196:199], v[78:81]
	v_mfma_f32_16x16x32_bf16 v[74:77], v[156:159], v[196:199], v[74:77]
	v_mfma_f32_16x16x32_bf16 v[126:129], v[152:155], v[176:179], v[126:129]
	v_mfma_f32_16x16x32_bf16 v[122:125], v[160:163], v[176:179], v[122:125]
	v_mfma_f32_16x16x32_bf16 v[110:113], v[152:155], v[184:187], v[110:113]
	v_mfma_f32_16x16x32_bf16 v[106:109], v[160:163], v[184:187], v[106:109]
	v_mfma_f32_16x16x32_bf16 v[94:97], v[152:155], v[192:195], v[94:97]
	v_mfma_f32_16x16x32_bf16 v[90:93], v[160:163], v[192:195], v[90:93]
	v_mfma_f32_16x16x32_bf16 v[78:81], v[152:155], v[200:203], v[78:81]
	v_mfma_f32_16x16x32_bf16 v[74:77], v[160:163], v[200:203], v[74:77]
	s_barrier
	s_add_i32 s3, 0, 0x1c000
	s_add_i32 s2, s2, s79
	v_add_u32_e32 v147, s3, v144
	v_lshl_add_u64 v[140:141], v[140:141], 0, s[58:59]
	s_mov_b32 m0, s2
	ds_read_b128 v[204:207], v147
	ds_read_b128 v[208:211], v147 offset:1024
	ds_read_b128 v[212:215], v147 offset:2048
	ds_read_b128 v[216:219], v147 offset:3072
	global_load_lds_dwordx4 v[140:141], off
	v_lshl_add_u64 v[140:141], v[164:165], 0, s[58:59]
	s_add_i32 m0, s2, 0x2000
	s_nop 0
	global_load_lds_dwordx4 v[140:141], off
	s_barrier
	s_waitcnt lgkmcnt(0)
	v_mfma_f32_16x16x32_bf16 v[118:121], v[204:207], v[168:171], v[118:121]
	v_mfma_f32_16x16x32_bf16 v[114:117], v[212:215], v[168:171], v[114:117]
	v_mfma_f32_16x16x32_bf16 v[102:105], v[204:207], v[180:183], v[102:105]
	v_mfma_f32_16x16x32_bf16 v[98:101], v[212:215], v[180:183], v[98:101]
	v_mfma_f32_16x16x32_bf16 v[86:89], v[204:207], v[188:191], v[86:89]
	v_mfma_f32_16x16x32_bf16 v[82:85], v[212:215], v[188:191], v[82:85]
	v_mfma_f32_16x16x32_bf16 v[70:73], v[204:207], v[196:199], v[70:73]
	v_mfma_f32_16x16x32_bf16 v[66:69], v[212:215], v[196:199], v[66:69]
	v_mfma_f32_16x16x32_bf16 v[118:121], v[208:211], v[176:179], v[118:121]
	v_mfma_f32_16x16x32_bf16 v[114:117], v[216:219], v[176:179], v[114:117]
	v_mfma_f32_16x16x32_bf16 v[102:105], v[208:211], v[184:187], v[102:105]
	v_mfma_f32_16x16x32_bf16 v[98:101], v[216:219], v[184:187], v[98:101]
	v_mfma_f32_16x16x32_bf16 v[86:89], v[208:211], v[192:195], v[86:89]
	v_mfma_f32_16x16x32_bf16 v[82:85], v[216:219], v[192:195], v[82:85]
	v_mfma_f32_16x16x32_bf16 v[70:73], v[208:211], v[200:203], v[70:73]
	v_mfma_f32_16x16x32_bf16 v[66:69], v[216:219], v[200:203], v[66:69]
	s_mov_b32 m0, s83
	v_lshl_add_u64 v[140:141], v[220:221], 0, s[58:59]
	s_barrier
	ds_read_b128 v[168:171], v146 offset:49152
	ds_read_b128 v[176:179], v146 offset:50176
	ds_read_b128 v[180:183], v146 offset:51200
	ds_read_b128 v[184:187], v146 offset:52224
	ds_read_b128 v[188:191], v146 offset:53248
	ds_read_b128 v[192:195], v146 offset:54272
	ds_read_b128 v[196:199], v146 offset:55296
	ds_read_b128 v[200:203], v146 offset:56320
	global_load_lds_dwordx4 v[140:141], off
	v_lshl_add_u64 v[140:141], v[222:223], 0, s[58:59]
	s_mov_b32 m0, s84
	s_nop 0
	global_load_lds_dwordx4 v[140:141], off
	s_barrier
; #define PG8_STAGE(bufoff, gbase, voff) do { _Pragma("unroll") for (int _i = 0; _i < 2; ++_i) \
;         __builtin_amdgcn_global_load_lds((const unsigned*)((const char*)(gbase) + (voff)[_i]), (LAS unsigned*)(lds + (bufoff) + ldsw + _i * 8192), 16, 0, 0); } while (0)
; #define PG8_LDA(dst, b, h) do { _Pragma("unroll") for (int m = 0; m < 4; ++m) _Pragma("unroll") for (int k = 0; k < 2; ++k) dst[m][k] = *(const LAS bf16x8*)(lds + PG8_SA(b, h) + aoff + m * 2048 + k * 1024); } while (0)
; #define PG8_LDB(dst, b, h) do { _Pragma("unroll") for (int n = 0; n < 2; ++n) _Pragma("unroll") for (int k = 0; k < 2; ++k) dst[n][k] = *(const LAS bf16x8*)(lds + PG8_SB(b, h) + boff + n * 2048 + k * 1024); } while (0)
; #define PG8_MMA(ai, bj, At, Bt) do { __builtin_amdgcn_s_setprio(1); _Pragma("unroll") for (int m = 0; m < 4; ++m) _Pragma("unroll") for (int n = 0; n < 2; ++n) _Pragma("unroll") for (int k = 0; k < 2; ++k) \
;         acc[ai][bj][m][n] = __builtin_amdgcn_mfma_f32_16x16x32_bf16(Bt[n][k], At[m][k], acc[ai][bj][m][n], 0, 0, 0); __builtin_amdgcn_s_setprio(0); } while (0)
; #define PG8_WAIT_V(n) asm volatile("s_waitcnt vmcnt(" #n ")" ::: "memory")
; #define PG8_WAIT_L(n) asm volatile("s_waitcnt lgkmcnt(" #n ")" ::: "memory")
; #define PG8_BAR __builtin_amdgcn_s_barrier()
; #define PG8_SCHED __builtin_amdgcn_sched_barrier(0)
; template <class Epi>
; DI void gemm_phase(int wv, LAS unsigned char* lds, const GemmD g, const Epi& E) {
;     ...
;             const bool last = (t == nt - 2);
;             const char* a1 = cA + (size_t)(t + 1) * kstep;
;             const char* a2 = last ? nA : cA + (size_t)(t + 2) * kstep; const char* b2 = last ? nB : cB + (size_t)(t + 2) * kstep;
;             const char* a3 = a2 + kstep; const char* b3 = b2 + kstep;
;             PG8_LDB(B0, 0, 0); PG8_SCHED; PG8_LDA(At, 0, 0); PG8_STAGE(PG8_SA(1, 1), a1 + hstepA, voffA);
;             PG8_WAIT_L(8); PG8_BAR; PG8_WAIT_L(0); PG8_MMA(0, 0, At, B0); PG8_BAR; PG8_SCHED;
;             PG8_LDB(B1, 0, 1); PG8_STAGE(PG8_SB(0, 0), b2, voffB);
;     ...
;             PG8_BAR; PG8_WAIT_L(0); PG8_MMA(1, 0, At, B0); PG8_BAR; PG8_SCHED;
;             PG8_STAGE(PG8_SB(1, 1), b3 + hstepB, voffB);
;             PG8_WAIT_V(6); PG8_BAR; PG8_MMA(1, 1, At, B1); PG8_BAR;
;         }
	s_waitcnt lgkmcnt(0)
	v_mfma_f32_16x16x32_bf16 v[62:65], v[148:151], v[168:171], v[62:65]
	v_mfma_f32_16x16x32_bf16 v[58:61], v[156:159], v[168:171], v[58:61]
	v_mfma_f32_16x16x32_bf16 v[46:49], v[148:151], v[180:183], v[46:49]
	v_mfma_f32_16x16x32_bf16 v[42:45], v[156:159], v[180:183], v[42:45]
	v_mfma_f32_16x16x32_bf16 v[30:33], v[148:151], v[188:191], v[30:33]
	v_mfma_f32_16x16x32_bf16 v[26:29], v[156:159], v[188:191], v[26:29]
	v_mfma_f32_16x16x32_bf16 v[14:17], v[148:151], v[196:199], v[14:17]
	v_mfma_f32_16x16x32_bf16 v[10:13], v[156:159], v[196:199], v[10:13]
	v_mfma_f32_16x16x32_bf16 v[62:65], v[152:155], v[176:179], v[62:65]
	v_mfma_f32_16x16x32_bf16 v[58:61], v[160:163], v[176:179], v[58:61]
	v_mfma_f32_16x16x32_bf16 v[46:49], v[152:155], v[184:187], v[46:49]
	v_mfma_f32_16x16x32_bf16 v[42:45], v[160:163], v[184:187], v[42:45]
	v_mfma_f32_16x16x32_bf16 v[30:33], v[152:155], v[192:195], v[30:33]
	v_mfma_f32_16x16x32_bf16 v[26:29], v[160:163], v[192:195], v[26:29]
	v_mfma_f32_16x16x32_bf16 v[14:17], v[152:155], v[200:203], v[14:17]
	v_mfma_f32_16x16x32_bf16 v[10:13], v[160:163], v[200:203], v[10:13]
	s_barrier
	s_add_u32 s18, s28, 0x40080
	s_addc_u32 s19, s29, 0
	s_add_i32 s2, s3, s79
	v_lshl_add_u64 v[140:141], s[18:19], 0, v[0:1]
	s_mov_b32 m0, s2
	s_nop 0
	global_load_lds_dwordx4 v[140:141], off
	v_lshl_add_u64 v[140:141], s[18:19], 0, v[134:135]
	s_add_i32 m0, s2, 0x2000
	s_nop 0
	global_load_lds_dwordx4 v[140:141], off
	s_waitcnt vmcnt(6)
	s_barrier
	v_mfma_f32_16x16x32_bf16 v[54:57], v[204:207], v[168:171], v[54:57]
	v_mfma_f32_16x16x32_bf16 v[50:53], v[212:215], v[168:171], v[50:53]
	v_mfma_f32_16x16x32_bf16 v[38:41], v[204:207], v[180:183], v[38:41]
	v_mfma_f32_16x16x32_bf16 v[34:37], v[212:215], v[180:183], v[34:37]
	v_mfma_f32_16x16x32_bf16 v[22:25], v[204:207], v[188:191], v[22:25]
	v_mfma_f32_16x16x32_bf16 v[18:21], v[212:215], v[188:191], v[18:21]
	v_mfma_f32_16x16x32_bf16 v[6:9], v[204:207], v[196:199], v[6:9]
	v_mfma_f32_16x16x32_bf16 v[2:5], v[212:215], v[196:199], v[2:5]
	v_mfma_f32_16x16x32_bf16 v[54:57], v[208:211], v[176:179], v[54:57]
	v_mfma_f32_16x16x32_bf16 v[50:53], v[216:219], v[176:179], v[50:53]
	v_mfma_f32_16x16x32_bf16 v[38:41], v[208:211], v[184:187], v[38:41]
	v_mfma_f32_16x16x32_bf16 v[34:37], v[216:219], v[184:187], v[34:37]
	v_mfma_f32_16x16x32_bf16 v[22:25], v[208:211], v[192:195], v[22:25]
	v_mfma_f32_16x16x32_bf16 v[18:21], v[216:219], v[192:195], v[18:21]
	v_mfma_f32_16x16x32_bf16 v[6:9], v[208:211], v[200:203], v[6:9]
	v_mfma_f32_16x16x32_bf16 v[2:5], v[216:219], v[200:203], v[2:5]
	s_add_i32 s41, s41, 2
	s_add_u32 s26, s26, 0x100
	s_addc_u32 s27, s27, 0
	s_add_u32 s36, s36, 0x100
	s_addc_u32 s38, s38, 0
	s_cmp_gt_u32 s41, 13
	s_barrier
	s_cbranch_scc0 .LBB0_490
	s_branch .Lgemm_epi_b
	.p2align 6
.LBB0_490:
	s_add_u32 s2, s26, 0xfffc0080
	s_addc_u32 s3, s27, -1
	s_add_i32 s18, 0, 0x10000
	v_add_u32_e32 v140, s18, v144
	ds_read_b128 v[148:151], v140
	ds_read_b128 v[152:155], v140 offset:1024
	ds_read_b128 v[156:159], v140 offset:2048
	ds_read_b128 v[160:163], v140 offset:3072
	s_cmp_eq_u32 s41, 12
	s_cselect_b32 s31, s7, s3
	s_cselect_b32 s30, s13, s2
	s_cselect_b32 s29, s16, s38
	s_cselect_b32 s28, s17, s36
	v_lshl_add_u64 v[140:141], s[26:27], 0, v[136:137]
	s_add_i32 m0, s25, 0xc000
	ds_read_b128 v[168:171], v146
	ds_read_b128 v[176:179], v146 offset:1024
	ds_read_b128 v[180:183], v146 offset:2048
	ds_read_b128 v[184:187], v146 offset:3072
	ds_read_b128 v[188:191], v146 offset:4096
	ds_read_b128 v[192:195], v146 offset:5120
	ds_read_b128 v[196:199], v146 offset:6144
	ds_read_b128 v[200:203], v146 offset:7168
	global_load_lds_dwordx4 v[140:141], off
	v_lshl_add_u64 v[140:141], s[26:27], 0, v[138:139]
	s_add_i32 m0, s25, 0xe000
	s_nop 0
	global_load_lds_dwordx4 v[140:141], off
	s_waitcnt lgkmcnt(8)
	s_barrier
	s_waitcnt lgkmcnt(0)
	v_mfma_f32_16x16x32_bf16 v[126:129], v[148:151], v[168:171], v[126:129]
	v_mfma_f32_16x16x32_bf16 v[122:125], v[156:159], v[168:171], v[122:125]
	v_mfma_f32_16x16x32_bf16 v[110:113], v[148:151], v[180:183], v[110:113]
	v_mfma_f32_16x16x32_bf16 v[106:109], v[156:159], v[180:183], v[106:109]
	v_mfma_f32_16x16x32_bf16 v[94:97], v[148:151], v[188:191], v[94:97]
	v_mfma_f32_16x16x32_bf16 v[90:93], v[156:159], v[188:191], v[90:93]
	v_mfma_f32_16x16x32_bf16 v[78:81], v[148:151], v[196:199], v[78:81]
	v_mfma_f32_16x16x32_bf16 v[74:77], v[156:159], v[196:199], v[74:77]
	v_mfma_f32_16x16x32_bf16 v[126:129], v[152:155], v[176:179], v[126:129]
	v_mfma_f32_16x16x32_bf16 v[122:125], v[160:163], v[176:179], v[122:125]
	v_mfma_f32_16x16x32_bf16 v[110:113], v[152:155], v[184:187], v[110:113]
	v_mfma_f32_16x16x32_bf16 v[106:109], v[160:163], v[184:187], v[106:109]
	v_mfma_f32_16x16x32_bf16 v[94:97], v[152:155], v[192:195], v[94:97]
	v_mfma_f32_16x16x32_bf16 v[90:93], v[160:163], v[192:195], v[90:93]
	v_mfma_f32_16x16x32_bf16 v[78:81], v[152:155], v[200:203], v[78:81]
	v_mfma_f32_16x16x32_bf16 v[74:77], v[160:163], v[200:203], v[74:77]
	s_barrier
	s_add_i32 s2, 0, 0x14000
	v_add_u32_e32 v140, s2, v144
	s_add_i32 s3, s18, s79
	ds_read_b128 v[204:207], v140
	ds_read_b128 v[208:211], v140 offset:1024
	ds_read_b128 v[212:215], v140 offset:2048
	ds_read_b128 v[216:219], v140 offset:3072
	v_lshl_add_u64 v[140:141], s[28:29], 0, v[0:1]
	s_mov_b32 m0, s3
	v_lshl_add_u64 v[164:165], s[28:29], 0, v[134:135]
	global_load_lds_dwordx4 v[140:141], off
	s_add_i32 m0, s3, 0x2000
	s_nop 0
	global_load_lds_dwordx4 v[164:165], off
	s_barrier
; #define PG8_STAGE(bufoff, gbase, voff) do { _Pragma("unroll") for (int _i = 0; _i < 2; ++_i) \
;         __builtin_amdgcn_global_load_lds((const unsigned*)((const char*)(gbase) + (voff)[_i]), (LAS unsigned*)(lds + (bufoff) + ldsw + _i * 8192), 16, 0, 0); } while (0)
; #define PG8_LDA(dst, b, h) do { _Pragma("unroll") for (int m = 0; m < 4; ++m) _Pragma("unroll") for (int k = 0; k < 2; ++k) dst[m][k] = *(const LAS bf16x8*)(lds + PG8_SA(b, h) + aoff + m * 2048 + k * 1024); } while (0)
; #define PG8_LDB(dst, b, h) do { _Pragma("unroll") for (int n = 0; n < 2; ++n) _Pragma("unroll") for (int k = 0; k < 2; ++k) dst[n][k] = *(const LAS bf16x8*)(lds + PG8_SB(b, h) + boff + n * 2048 + k * 1024); } while (0)
; #define PG8_MMA(ai, bj, At, Bt) do { __builtin_amdgcn_s_setprio(1); _Pragma("unroll") for (int m = 0; m < 4; ++m) _Pragma("unroll") for (int n = 0; n < 2; ++n) _Pragma("unroll") for (int k = 0; k < 2; ++k) \
;         acc[ai][bj][m][n] = __builtin_amdgcn_mfma_f32_16x16x32_bf16(Bt[n][k], At[m][k], acc[ai][bj][m][n], 0, 0, 0); __builtin_amdgcn_s_setprio(0); } while (0)
; #define PG8_WAIT_V(n) asm volatile("s_waitcnt vmcnt(" #n ")" ::: "memory")
; #define PG8_WAIT_L(n) asm volatile("s_waitcnt lgkmcnt(" #n ")" ::: "memory")
; #define PG8_BAR __builtin_amdgcn_s_barrier()
; #define PG8_SCHED __builtin_amdgcn_sched_barrier(0)
; template <class Epi>
; DI void gemm_phase(int wv, LAS unsigned char* lds, const GemmD g, const Epi& E) {
;     ...
;             PG8_BAR; PG8_WAIT_L(0); PG8_MMA(0, 1, At, B1); PG8_BAR;
;             PG8_LDA(At, 0, 1); PG8_STAGE(PG8_SA(0, 0), a2, voffA);
;             PG8_BAR; PG8_WAIT_L(0); PG8_MMA(1, 0, At, B0); PG8_BAR; PG8_SCHED;
;             PG8_STAGE(PG8_SB(0, 1), b2 + hstepB, voffB);
;             PG8_WAIT_V(6); PG8_BAR; PG8_MMA(1, 1, At, B1); PG8_BAR;
;             PG8_LDB(B0, 1, 0); PG8_SCHED; PG8_LDA(At, 1, 0); PG8_STAGE(PG8_SA(0, 1), a2 + hstepA, voffA);
;             PG8_WAIT_L(8); PG8_BAR; PG8_WAIT_L(0); PG8_MMA(0, 0, At, B0); PG8_BAR; PG8_SCHED;
	s_waitcnt lgkmcnt(0)
	v_mfma_f32_16x16x32_bf16 v[118:121], v[204:207], v[168:171], v[118:121]
	v_mfma_f32_16x16x32_bf16 v[114:117], v[212:215], v[168:171], v[114:117]
	v_mfma_f32_16x16x32_bf16 v[102:105], v[204:207], v[180:183], v[102:105]
	v_mfma_f32_16x16x32_bf16 v[98:101], v[212:215], v[180:183], v[98:101]
	v_mfma_f32_16x16x32_bf16 v[86:89], v[204:207], v[188:191], v[86:89]
	v_mfma_f32_16x16x32_bf16 v[82:85], v[212:215], v[188:191], v[82:85]
	v_mfma_f32_16x16x32_bf16 v[70:73], v[204:207], v[196:199], v[70:73]
	v_mfma_f32_16x16x32_bf16 v[66:69], v[212:215], v[196:199], v[66:69]
	v_mfma_f32_16x16x32_bf16 v[118:121], v[208:211], v[176:179], v[118:121]
	v_mfma_f32_16x16x32_bf16 v[114:117], v[216:219], v[176:179], v[114:117]
	v_mfma_f32_16x16x32_bf16 v[102:105], v[208:211], v[184:187], v[102:105]
	v_mfma_f32_16x16x32_bf16 v[98:101], v[216:219], v[184:187], v[98:101]
	v_mfma_f32_16x16x32_bf16 v[86:89], v[208:211], v[192:195], v[86:89]
	v_mfma_f32_16x16x32_bf16 v[82:85], v[216:219], v[192:195], v[82:85]
	v_mfma_f32_16x16x32_bf16 v[70:73], v[208:211], v[200:203], v[70:73]
	v_mfma_f32_16x16x32_bf16 v[66:69], v[216:219], v[200:203], v[66:69]
	s_mov_b32 m0, s25
	v_lshl_add_u64 v[220:221], s[30:31], 0, v[130:131]
	s_barrier
	ds_read_b128 v[168:171], v146 offset:16384
	ds_read_b128 v[176:179], v146 offset:17408
	ds_read_b128 v[180:183], v146 offset:18432
	ds_read_b128 v[184:187], v146 offset:19456
	ds_read_b128 v[188:191], v146 offset:20480
	ds_read_b128 v[192:195], v146 offset:21504
	ds_read_b128 v[196:199], v146 offset:22528
	ds_read_b128 v[200:203], v146 offset:23552
	global_load_lds_dwordx4 v[220:221], off
	v_lshl_add_u64 v[222:223], s[30:31], 0, v[132:133]
	s_mov_b32 m0, s80
	s_nop 0
	global_load_lds_dwordx4 v[222:223], off
	s_barrier
	s_waitcnt lgkmcnt(0)
	v_mfma_f32_16x16x32_bf16 v[62:65], v[148:151], v[168:171], v[62:65]
	v_mfma_f32_16x16x32_bf16 v[58:61], v[156:159], v[168:171], v[58:61]
	v_mfma_f32_16x16x32_bf16 v[46:49], v[148:151], v[180:183], v[46:49]
	v_mfma_f32_16x16x32_bf16 v[42:45], v[156:159], v[180:183], v[42:45]
	v_mfma_f32_16x16x32_bf16 v[30:33], v[148:151], v[188:191], v[30:33]
	v_mfma_f32_16x16x32_bf16 v[26:29], v[156:159], v[188:191], v[26:29]
	v_mfma_f32_16x16x32_bf16 v[14:17], v[148:151], v[196:199], v[14:17]
	v_mfma_f32_16x16x32_bf16 v[10:13], v[156:159], v[196:199], v[10:13]
	v_mfma_f32_16x16x32_bf16 v[62:65], v[152:155], v[176:179], v[62:65]
	v_mfma_f32_16x16x32_bf16 v[58:61], v[160:163], v[176:179], v[58:61]
	v_mfma_f32_16x16x32_bf16 v[46:49], v[152:155], v[184:187], v[46:49]
	v_mfma_f32_16x16x32_bf16 v[42:45], v[160:163], v[184:187], v[42:45]
	v_mfma_f32_16x16x32_bf16 v[30:33], v[152:155], v[192:195], v[30:33]
	v_mfma_f32_16x16x32_bf16 v[26:29], v[160:163], v[192:195], v[26:29]
	v_mfma_f32_16x16x32_bf16 v[14:17], v[152:155], v[200:203], v[14:17]
	v_mfma_f32_16x16x32_bf16 v[10:13], v[160:163], v[200:203], v[10:13]
	s_barrier
	s_add_u32 s18, s28, 0x40000
	s_addc_u32 s19, s29, 0
	s_add_i32 s2, s2, s79
	v_lshl_add_u64 v[148:149], s[18:19], 0, v[0:1]
	s_mov_b32 m0, s2
	s_nop 0
	global_load_lds_dwordx4 v[148:149], off
	v_lshl_add_u64 v[148:149], s[18:19], 0, v[134:135]
	s_add_i32 m0, s2, 0x2000
	s_nop 0
	global_load_lds_dwordx4 v[148:149], off
	s_waitcnt vmcnt(6)
	s_barrier
	v_mfma_f32_16x16x32_bf16 v[54:57], v[204:207], v[168:171], v[54:57]
	v_mfma_f32_16x16x32_bf16 v[50:53], v[212:215], v[168:171], v[50:53]
	v_mfma_f32_16x16x32_bf16 v[38:41], v[204:207], v[180:183], v[38:41]
	v_mfma_f32_16x16x32_bf16 v[34:37], v[212:215], v[180:183], v[34:37]
	v_mfma_f32_16x16x32_bf16 v[22:25], v[204:207], v[188:191], v[22:25]
	v_mfma_f32_16x16x32_bf16 v[18:21], v[212:215], v[188:191], v[18:21]
	v_mfma_f32_16x16x32_bf16 v[6:9], v[204:207], v[196:199], v[6:9]
	v_mfma_f32_16x16x32_bf16 v[2:5], v[212:215], v[196:199], v[2:5]
	v_mfma_f32_16x16x32_bf16 v[54:57], v[208:211], v[176:179], v[54:57]
	v_mfma_f32_16x16x32_bf16 v[50:53], v[216:219], v[176:179], v[50:53]
	v_mfma_f32_16x16x32_bf16 v[38:41], v[208:211], v[184:187], v[38:41]
	v_mfma_f32_16x16x32_bf16 v[34:37], v[216:219], v[184:187], v[34:37]
	v_mfma_f32_16x16x32_bf16 v[22:25], v[208:211], v[192:195], v[22:25]
	v_mfma_f32_16x16x32_bf16 v[18:21], v[216:219], v[192:195], v[18:21]
	v_mfma_f32_16x16x32_bf16 v[6:9], v[208:211], v[200:203], v[6:9]
	v_mfma_f32_16x16x32_bf16 v[2:5], v[216:219], v[200:203], v[2:5]
	s_add_i32 s2, 0, 0x18000
	v_add_u32_e32 v147, s2, v144
	s_barrier
	ds_read_b128 v[148:151], v147
	ds_read_b128 v[152:155], v147 offset:1024
	ds_read_b128 v[156:159], v147 offset:2048
	ds_read_b128 v[160:163], v147 offset:3072
	s_add_u32 s18, s30, 0x40000
	s_addc_u32 s19, s31, 0
	s_mov_b32 m0, s81
	v_lshl_add_u64 v[204:205], s[18:19], 0, v[130:131]
	ds_read_b128 v[168:171], v146 offset:32768
	ds_read_b128 v[176:179], v146 offset:33792
	ds_read_b128 v[180:183], v146 offset:34816
	ds_read_b128 v[184:187], v146 offset:35840
	ds_read_b128 v[188:191], v146 offset:36864
	ds_read_b128 v[192:195], v146 offset:37888
	ds_read_b128 v[196:199], v146 offset:38912
	ds_read_b128 v[200:203], v146 offset:39936
	global_load_lds_dwordx4 v[204:205], off
	v_lshl_add_u64 v[204:205], s[18:19], 0, v[132:133]
	s_mov_b32 m0, s82
	s_nop 0
	global_load_lds_dwordx4 v[204:205], off
	s_waitcnt lgkmcnt(8)
	s_barrier
; #define PG8_STAGE(bufoff, gbase, voff) do { _Pragma("unroll") for (int _i = 0; _i < 2; ++_i) \
;         __builtin_amdgcn_global_load_lds((const unsigned*)((const char*)(gbase) + (voff)[_i]), (LAS unsigned*)(lds + (bufoff) + ldsw + _i * 8192), 16, 0, 0); } while (0)
; #define PG8_LDA(dst, b, h) do { _Pragma("unroll") for (int m = 0; m < 4; ++m) _Pragma("unroll") for (int k = 0; k < 2; ++k) dst[m][k] = *(const LAS bf16x8*)(lds + PG8_SA(b, h) + aoff + m * 2048 + k * 1024); } while (0)
; #define PG8_LDB(dst, b, h) do { _Pragma("unroll") for (int n = 0; n < 2; ++n) _Pragma("unroll") for (int k = 0; k < 2; ++k) dst[n][k] = *(const LAS bf16x8*)(lds + PG8_SB(b, h) + boff + n * 2048 + k * 1024); } while (0)
; #define PG8_MMA(ai, bj, At, Bt) do { __builtin_amdgcn_s_setprio(1); _Pragma("unroll") for (int m = 0; m < 4; ++m) _Pragma("unroll") for (int n = 0; n < 2; ++n) _Pragma("unroll") for (int k = 0; k < 2; ++k) \
;         acc[ai][bj][m][n] = __builtin_amdgcn_mfma_f32_16x16x32_bf16(Bt[n][k], At[m][k], acc[ai][bj][m][n], 0, 0, 0); __builtin_amdgcn_s_setprio(0); } while (0)
; #define PG8_WAIT_V(n) asm volatile("s_waitcnt vmcnt(" #n ")" ::: "memory")
; #define PG8_WAIT_L(n) asm volatile("s_waitcnt lgkmcnt(" #n ")" ::: "memory")
; #define PG8_BAR __builtin_amdgcn_s_barrier()
; #define PG8_SCHED __builtin_amdgcn_sched_barrier(0)
; template <class Epi>
; DI void gemm_phase(int wv, LAS unsigned char* lds, const GemmD g, const Epi& E) {
;     ...
;             PG8_WAIT_L(8); PG8_BAR; PG8_WAIT_L(0); PG8_MMA(0, 0, At, B0); PG8_BAR; PG8_SCHED;
;             PG8_LDB(B1, 1, 1); PG8_STAGE(PG8_SB(1, 0), b3, voffB);
;             PG8_BAR; PG8_WAIT_L(0); PG8_MMA(0, 1, At, B1); PG8_BAR;
;             PG8_LDA(At, 1, 1); PG8_STAGE(PG8_SA(1, 0), a3, voffA);
;             PG8_BAR; PG8_WAIT_L(0); PG8_MMA(1, 0, At, B0); PG8_BAR; PG8_SCHED;
;             PG8_STAGE(PG8_SB(1, 1), b3 + hstepB, voffB);
;             PG8_WAIT_V(6); PG8_BAR; PG8_MMA(1, 1, At, B1); PG8_BAR;
;         }
	s_waitcnt lgkmcnt(0)
	v_mfma_f32_16x16x32_bf16 v[126:129], v[148:151], v[168:171], v[126:129]
	v_mfma_f32_16x16x32_bf16 v[122:125], v[156:159], v[168:171], v[122:125]
	v_mfma_f32_16x16x32_bf16 v[110:113], v[148:151], v[180:183], v[110:113]
	v_mfma_f32_16x16x32_bf16 v[106:109], v[156:159], v[180:183], v[106:109]
	v_mfma_f32_16x16x32_bf16 v[94:97], v[148:151], v[188:191], v[94:97]
	v_mfma_f32_16x16x32_bf16 v[90:93], v[156:159], v[188:191], v[90:93]
	v_mfma_f32_16x16x32_bf16 v[78:81], v[148:151], v[196:199], v[78:81]
	v_mfma_f32_16x16x32_bf16 v[74:77], v[156:159], v[196:199], v[74:77]
	v_mfma_f32_16x16x32_bf16 v[126:129], v[152:155], v[176:179], v[126:129]
	v_mfma_f32_16x16x32_bf16 v[122:125], v[160:163], v[176:179], v[122:125]
	v_mfma_f32_16x16x32_bf16 v[110:113], v[152:155], v[184:187], v[110:113]
	v_mfma_f32_16x16x32_bf16 v[106:109], v[160:163], v[184:187], v[106:109]
	v_mfma_f32_16x16x32_bf16 v[94:97], v[152:155], v[192:195], v[94:97]
	v_mfma_f32_16x16x32_bf16 v[90:93], v[160:163], v[192:195], v[90:93]
	v_mfma_f32_16x16x32_bf16 v[78:81], v[152:155], v[200:203], v[78:81]
	v_mfma_f32_16x16x32_bf16 v[74:77], v[160:163], v[200:203], v[74:77]
	s_barrier
	s_add_i32 s3, 0, 0x1c000
	s_add_i32 s2, s2, s79
	v_add_u32_e32 v147, s3, v144
	v_lshl_add_u64 v[140:141], v[140:141], 0, s[58:59]
	s_mov_b32 m0, s2
	ds_read_b128 v[204:207], v147
	ds_read_b128 v[208:211], v147 offset:1024
	ds_read_b128 v[212:215], v147 offset:2048
	ds_read_b128 v[216:219], v147 offset:3072
	global_load_lds_dwordx4 v[140:141], off
	v_lshl_add_u64 v[140:141], v[164:165], 0, s[58:59]
	s_add_i32 m0, s2, 0x2000
	s_nop 0
	global_load_lds_dwordx4 v[140:141], off
	s_barrier
	s_waitcnt lgkmcnt(0)
	v_mfma_f32_16x16x32_bf16 v[118:121], v[204:207], v[168:171], v[118:121]
	v_mfma_f32_16x16x32_bf16 v[114:117], v[212:215], v[168:171], v[114:117]
	v_mfma_f32_16x16x32_bf16 v[102:105], v[204:207], v[180:183], v[102:105]
	v_mfma_f32_16x16x32_bf16 v[98:101], v[212:215], v[180:183], v[98:101]
	v_mfma_f32_16x16x32_bf16 v[86:89], v[204:207], v[188:191], v[86:89]
	v_mfma_f32_16x16x32_bf16 v[82:85], v[212:215], v[188:191], v[82:85]
	v_mfma_f32_16x16x32_bf16 v[70:73], v[204:207], v[196:199], v[70:73]
	v_mfma_f32_16x16x32_bf16 v[66:69], v[212:215], v[196:199], v[66:69]
	v_mfma_f32_16x16x32_bf16 v[118:121], v[208:211], v[176:179], v[118:121]
	v_mfma_f32_16x16x32_bf16 v[114:117], v[216:219], v[176:179], v[114:117]
	v_mfma_f32_16x16x32_bf16 v[102:105], v[208:211], v[184:187], v[102:105]
	v_mfma_f32_16x16x32_bf16 v[98:101], v[216:219], v[184:187], v[98:101]
	v_mfma_f32_16x16x32_bf16 v[86:89], v[208:211], v[192:195], v[86:89]
	v_mfma_f32_16x16x32_bf16 v[82:85], v[216:219], v[192:195], v[82:85]
	v_mfma_f32_16x16x32_bf16 v[70:73], v[208:211], v[200:203], v[70:73]
	v_mfma_f32_16x16x32_bf16 v[66:69], v[216:219], v[200:203], v[66:69]
	s_mov_b32 m0, s83
	v_lshl_add_u64 v[140:141], v[220:221], 0, s[58:59]
	s_barrier
	ds_read_b128 v[168:171], v146 offset:49152
	ds_read_b128 v[176:179], v146 offset:50176
	ds_read_b128 v[180:183], v146 offset:51200
	ds_read_b128 v[184:187], v146 offset:52224
	ds_read_b128 v[188:191], v146 offset:53248
	ds_read_b128 v[192:195], v146 offset:54272
	ds_read_b128 v[196:199], v146 offset:55296
	ds_read_b128 v[200:203], v146 offset:56320
	global_load_lds_dwordx4 v[140:141], off
	v_lshl_add_u64 v[140:141], v[222:223], 0, s[58:59]
	s_mov_b32 m0, s84
	s_nop 0
	global_load_lds_dwordx4 v[140:141], off
	s_barrier
	s_waitcnt lgkmcnt(0)
	v_mfma_f32_16x16x32_bf16 v[62:65], v[148:151], v[168:171], v[62:65]
	v_mfma_f32_16x16x32_bf16 v[58:61], v[156:159], v[168:171], v[58:61]
	v_mfma_f32_16x16x32_bf16 v[46:49], v[148:151], v[180:183], v[46:49]
	v_mfma_f32_16x16x32_bf16 v[42:45], v[156:159], v[180:183], v[42:45]
	v_mfma_f32_16x16x32_bf16 v[30:33], v[148:151], v[188:191], v[30:33]
	v_mfma_f32_16x16x32_bf16 v[26:29], v[156:159], v[188:191], v[26:29]
	v_mfma_f32_16x16x32_bf16 v[14:17], v[148:151], v[196:199], v[14:17]
	v_mfma_f32_16x16x32_bf16 v[10:13], v[156:159], v[196:199], v[10:13]
	v_mfma_f32_16x16x32_bf16 v[62:65], v[152:155], v[176:179], v[62:65]
	v_mfma_f32_16x16x32_bf16 v[58:61], v[160:163], v[176:179], v[58:61]
	v_mfma_f32_16x16x32_bf16 v[46:49], v[152:155], v[184:187], v[46:49]
	v_mfma_f32_16x16x32_bf16 v[42:45], v[160:163], v[184:187], v[42:45]
	v_mfma_f32_16x16x32_bf16 v[30:33], v[152:155], v[192:195], v[30:33]
	v_mfma_f32_16x16x32_bf16 v[26:29], v[160:163], v[192:195], v[26:29]
	v_mfma_f32_16x16x32_bf16 v[14:17], v[152:155], v[200:203], v[14:17]
	v_mfma_f32_16x16x32_bf16 v[10:13], v[160:163], v[200:203], v[10:13]
	s_barrier
	s_add_u32 s18, s28, 0x40080
	s_addc_u32 s19, s29, 0
	s_add_i32 s2, s3, s79
	v_lshl_add_u64 v[140:141], s[18:19], 0, v[0:1]
	s_mov_b32 m0, s2
	s_nop 0
	global_load_lds_dwordx4 v[140:141], off
	v_lshl_add_u64 v[140:141], s[18:19], 0, v[134:135]
	s_add_i32 m0, s2, 0x2000
	s_nop 0
	global_load_lds_dwordx4 v[140:141], off
	s_waitcnt vmcnt(6)
	s_barrier
	v_mfma_f32_16x16x32_bf16 v[54:57], v[204:207], v[168:171], v[54:57]
	v_mfma_f32_16x16x32_bf16 v[50:53], v[212:215], v[168:171], v[50:53]
	v_mfma_f32_16x16x32_bf16 v[38:41], v[204:207], v[180:183], v[38:41]
	v_mfma_f32_16x16x32_bf16 v[34:37], v[212:215], v[180:183], v[34:37]
	v_mfma_f32_16x16x32_bf16 v[22:25], v[204:207], v[188:191], v[22:25]
	v_mfma_f32_16x16x32_bf16 v[18:21], v[212:215], v[188:191], v[18:21]
	v_mfma_f32_16x16x32_bf16 v[6:9], v[204:207], v[196:199], v[6:9]
	v_mfma_f32_16x16x32_bf16 v[2:5], v[212:215], v[196:199], v[2:5]
	v_mfma_f32_16x16x32_bf16 v[54:57], v[208:211], v[176:179], v[54:57]
	v_mfma_f32_16x16x32_bf16 v[50:53], v[216:219], v[176:179], v[50:53]
	v_mfma_f32_16x16x32_bf16 v[38:41], v[208:211], v[184:187], v[38:41]
	v_mfma_f32_16x16x32_bf16 v[34:37], v[216:219], v[184:187], v[34:37]
	v_mfma_f32_16x16x32_bf16 v[22:25], v[208:211], v[192:195], v[22:25]
	v_mfma_f32_16x16x32_bf16 v[18:21], v[216:219], v[192:195], v[18:21]
	v_mfma_f32_16x16x32_bf16 v[6:9], v[208:211], v[200:203], v[6:9]
	v_mfma_f32_16x16x32_bf16 v[2:5], v[216:219], v[200:203], v[2:5]
	s_add_i32 s41, s41, 2
	s_add_u32 s26, s26, 0x100
	s_addc_u32 s27, s27, 0
	s_add_u32 s36, s36, 0x100
	s_addc_u32 s38, s38, 0
	s_cmp_gt_u32 s41, 13
	s_barrier
	s_cbranch_scc0 .LBB0_490

; #define PG8_STAGE(bufoff, gbase, voff) do { _Pragma("unroll") for (int _i = 0; _i < 2; ++_i) \
;         __builtin_amdgcn_global_load_lds((const unsigned*)((const char*)(gbase) + (voff)[_i]), (LAS unsigned*)(lds + (bufoff) + ldsw + _i * 8192), 16, 0, 0); } while (0)
; #define PG8_LDA(dst, b, h) do { _Pragma("unroll") for (int m = 0; m < 4; ++m) _Pragma("unroll") for (int k = 0; k < 2; ++k) dst[m][k] = *(const LAS bf16x8*)(lds + PG8_SA(b, h) + aoff + m * 2048 + k * 1024); } while (0)
; #define PG8_LDB(dst, b, h) do { _Pragma("unroll") for (int n = 0; n < 2; ++n) _Pragma("unroll") for (int k = 0; k < 2; ++k) dst[n][k] = *(const LAS bf16x8*)(lds + PG8_SB(b, h) + boff + n * 2048 + k * 1024); } while (0)
; #define PG8_MMA(ai, bj, At, Bt) do { __builtin_amdgcn_s_setprio(1); _Pragma("unroll") for (int m = 0; m < 4; ++m) _Pragma("unroll") for (int n = 0; n < 2; ++n) _Pragma("unroll") for (int k = 0; k < 2; ++k) \
;         acc[ai][bj][m][n] = __builtin_amdgcn_mfma_f32_16x16x32_bf16(Bt[n][k], At[m][k], acc[ai][bj][m][n], 0, 0, 0); __builtin_amdgcn_s_setprio(0); } while (0)
; #define PG8_WAIT_L(n) asm volatile("s_waitcnt lgkmcnt(" #n ")" ::: "memory")
; template <class Epi>
; DI void gemm_phase(int wv, LAS unsigned char* lds, const GemmD g, const Epi& E) {
;     ...
;         const bool has_next = S.next(ui + 1, nxt);
;         const char* nA = has_next ? (const char*)g.A + (size_t)nxt.pm * 256 * g.lda * 2 : cA; const char* nB = has_next ? (const char*)g.Bt + PG8_BROW(nxt.pn) * (size_t)g.ldb * 2 : cB;
;         for (int t = 0; t < nt; t += 2) {
;             const bool last = (t == nt - 2);
;             const char* a1 = cA + (size_t)(t + 1) * kstep;
;             const char* a2 = last ? nA : cA + (size_t)(t + 2) * kstep; const char* b2 = last ? nB : cB + (size_t)(t + 2) * kstep;
;             const char* a3 = a2 + kstep; const char* b3 = b2 + kstep;
;             PG8_LDB(B0, 0, 0); PG8_SCHED; PG8_LDA(At, 0, 0); PG8_STAGE(PG8_SA(1, 1), a1 + hstepA, voffA);
;             PG8_WAIT_L(8); PG8_BAR; PG8_WAIT_L(0); PG8_MMA(0, 0, At, B0); PG8_BAR; PG8_SCHED;
;             PG8_LDB(B1, 0, 1); PG8_STAGE(PG8_SB(0, 0), b2, voffB);
;             PG8_BAR; PG8_WAIT_L(0); PG8_MMA(0, 1, At, B1); PG8_BAR;
;             PG8_LDA(At, 0, 1); PG8_STAGE(PG8_SA(0, 0), a2, voffA);
;             PG8_BAR; PG8_WAIT_L(0); PG8_MMA(1, 0, At, B0); PG8_BAR; PG8_SCHED;
.LBB0_543:
	s_ashr_i32 s23, s22, 31
	s_lshl_b64 s[18:19], s[22:23], s85
	v_cmp_lt_i64_e32 vcc, s[24:25], v[174:175]
	s_add_u32 s24, s81, s18
	s_addc_u32 s25, s80, s19
	s_and_b64 s[18:19], vcc, exec
	s_cselect_b32 s23, s25, s29
	s_cselect_b32 s68, s24, s28
	s_lshl_b32 s18, s55, 8
	s_ashr_i32 s19, s18, 31
	s_lshl_b64 s[18:19], s[18:19], s9
	s_add_u32 s26, s82, s18
	s_addc_u32 s27, s83, s19
	s_and_b64 s[18:19], vcc, exec
	s_cselect_b32 vcc_lo, s27, s31
	s_cselect_b32 vcc_hi, s26, s30
	s_add_u32 s28, s28, 0x80
	s_addc_u32 s29, s29, 0
	s_add_u32 s37, s30, 0x100
	s_addc_u32 s18, s31, 0
	s_mov_b32 s19, 0
	s_add_i32 s95, s19, 2
	s_add_u32 s2, s28, 0x80
	s_addc_u32 s3, s29, 0
	s_add_i32 s94, 0, 0x10000
	v_add_u32_e32 v145, s94, v141
	ds_read_b128 v[146:149], v145
	ds_read_b128 v[150:153], v145 offset:1024
	ds_read_b128 v[154:157], v145 offset:2048
	ds_read_b128 v[158:161], v145 offset:3072
	s_cmp_eq_u32 s17, s19
	s_cselect_b32 s31, s23, s3
	s_cselect_b32 s30, s68, s2
	s_cselect_b32 s35, vcc_lo, s18
	s_cselect_b32 s34, vcc_hi, s37
	v_lshl_add_u64 v[200:201], s[28:29], 0, v[136:137]
	s_add_i32 m0, s86, 0xc000
	ds_read_b128 v[162:165], v144
	ds_read_b128 v[168:171], v144 offset:1024
	ds_read_b128 v[176:179], v144 offset:2048
	ds_read_b128 v[180:183], v144 offset:3072
	ds_read_b128 v[184:187], v144 offset:4096
	ds_read_b128 v[188:191], v144 offset:5120
	ds_read_b128 v[192:195], v144 offset:6144
	ds_read_b128 v[196:199], v144 offset:7168
	global_load_lds_dwordx4 v[200:201], off
	v_lshl_add_u64 v[200:201], s[28:29], 0, v[138:139]
	s_add_i32 m0, s86, 0xe000
	s_nop 0
	global_load_lds_dwordx4 v[200:201], off
	s_waitcnt lgkmcnt(8)
	s_barrier
	s_waitcnt lgkmcnt(0)
	v_mfma_f32_16x16x32_bf16 v[126:129], v[146:149], v[162:165], 0
	v_mfma_f32_16x16x32_bf16 v[122:125], v[154:157], v[162:165], 0
	v_mfma_f32_16x16x32_bf16 v[118:121], v[146:149], v[176:179], 0
	v_mfma_f32_16x16x32_bf16 v[114:117], v[154:157], v[176:179], 0
	v_mfma_f32_16x16x32_bf16 v[102:105], v[146:149], v[184:187], 0
	v_mfma_f32_16x16x32_bf16 v[98:101], v[154:157], v[184:187], 0
	v_mfma_f32_16x16x32_bf16 v[86:89], v[146:149], v[192:195], 0
	v_mfma_f32_16x16x32_bf16 v[82:85], v[154:157], v[192:195], 0
	v_mfma_f32_16x16x32_bf16 v[126:129], v[150:153], v[168:171], v[126:129]
	v_mfma_f32_16x16x32_bf16 v[122:125], v[158:161], v[168:171], v[122:125]
	v_mfma_f32_16x16x32_bf16 v[118:121], v[150:153], v[180:183], v[118:121]
	v_mfma_f32_16x16x32_bf16 v[114:117], v[158:161], v[180:183], v[114:117]
	v_mfma_f32_16x16x32_bf16 v[102:105], v[150:153], v[188:191], v[102:105]
	v_mfma_f32_16x16x32_bf16 v[98:101], v[158:161], v[188:191], v[98:101]
	v_mfma_f32_16x16x32_bf16 v[86:89], v[150:153], v[196:199], v[86:89]
	v_mfma_f32_16x16x32_bf16 v[82:85], v[158:161], v[196:199], v[82:85]
	s_barrier
	s_add_i32 s2, 0, 0x14000
	s_add_i32 s3, s94, s84
	v_add_u32_e32 v145, s2, v141
	v_lshl_add_u64 v[216:217], s[34:35], 0, v[0:1]
	s_mov_b32 m0, s3
	ds_read_b128 v[200:203], v145
	ds_read_b128 v[204:207], v145 offset:1024
	ds_read_b128 v[208:211], v145 offset:2048
	ds_read_b128 v[212:215], v145 offset:3072
	global_load_lds_dwordx4 v[216:217], off
	v_lshl_add_u64 v[218:219], s[34:35], 0, v[134:135]
	s_add_i32 m0, s3, 0x2000
	s_nop 0
	global_load_lds_dwordx4 v[218:219], off
	s_barrier
	s_waitcnt lgkmcnt(0)
	v_mfma_f32_16x16x32_bf16 v[110:113], v[200:203], v[162:165], 0
	v_mfma_f32_16x16x32_bf16 v[106:109], v[208:211], v[162:165], 0
	v_mfma_f32_16x16x32_bf16 v[94:97], v[200:203], v[176:179], 0
	v_mfma_f32_16x16x32_bf16 v[90:93], v[208:211], v[176:179], 0
	v_mfma_f32_16x16x32_bf16 v[78:81], v[200:203], v[184:187], 0
	v_mfma_f32_16x16x32_bf16 v[74:77], v[208:211], v[184:187], 0
	v_mfma_f32_16x16x32_bf16 v[70:73], v[200:203], v[192:195], 0
	v_mfma_f32_16x16x32_bf16 v[66:69], v[208:211], v[192:195], 0
	v_mfma_f32_16x16x32_bf16 v[110:113], v[204:207], v[168:171], v[110:113]
	v_mfma_f32_16x16x32_bf16 v[106:109], v[212:215], v[168:171], v[106:109]
	v_mfma_f32_16x16x32_bf16 v[94:97], v[204:207], v[180:183], v[94:97]
	v_mfma_f32_16x16x32_bf16 v[90:93], v[212:215], v[180:183], v[90:93]
	v_mfma_f32_16x16x32_bf16 v[78:81], v[204:207], v[188:191], v[78:81]
	v_mfma_f32_16x16x32_bf16 v[74:77], v[212:215], v[188:191], v[74:77]
	v_mfma_f32_16x16x32_bf16 v[70:73], v[204:207], v[196:199], v[70:73]
	v_mfma_f32_16x16x32_bf16 v[66:69], v[212:215], v[196:199], v[66:69]
	s_mov_b32 m0, s86
	v_lshl_add_u64 v[220:221], s[30:31], 0, v[130:131]
	s_barrier
	ds_read_b128 v[162:165], v144 offset:16384
	ds_read_b128 v[168:171], v144 offset:17408
	ds_read_b128 v[176:179], v144 offset:18432
	ds_read_b128 v[180:183], v144 offset:19456
	ds_read_b128 v[184:187], v144 offset:20480
	ds_read_b128 v[188:191], v144 offset:21504
	ds_read_b128 v[192:195], v144 offset:22528
	ds_read_b128 v[196:199], v144 offset:23552
	global_load_lds_dwordx4 v[220:221], off
	v_lshl_add_u64 v[222:223], s[30:31], 0, v[132:133]
	s_mov_b32 m0, s87
	s_nop 0
	global_load_lds_dwordx4 v[222:223], off
	s_barrier
	s_waitcnt lgkmcnt(0)
	v_mfma_f32_16x16x32_bf16 v[62:65], v[146:149], v[162:165], 0
	v_mfma_f32_16x16x32_bf16 v[58:61], v[154:157], v[162:165], 0
	v_mfma_f32_16x16x32_bf16 v[54:57], v[146:149], v[176:179], 0
	v_mfma_f32_16x16x32_bf16 v[50:53], v[154:157], v[176:179], 0
	v_mfma_f32_16x16x32_bf16 v[38:41], v[146:149], v[184:187], 0
	v_mfma_f32_16x16x32_bf16 v[34:37], v[154:157], v[184:187], 0
	v_mfma_f32_16x16x32_bf16 v[22:25], v[146:149], v[192:195], 0
	v_mfma_f32_16x16x32_bf16 v[18:21], v[154:157], v[192:195], 0
	v_mfma_f32_16x16x32_bf16 v[62:65], v[150:153], v[168:171], v[62:65]
	v_mfma_f32_16x16x32_bf16 v[58:61], v[158:161], v[168:171], v[58:61]
	v_mfma_f32_16x16x32_bf16 v[54:57], v[150:153], v[180:183], v[54:57]
	v_mfma_f32_16x16x32_bf16 v[50:53], v[158:161], v[180:183], v[50:53]
	v_mfma_f32_16x16x32_bf16 v[38:41], v[150:153], v[188:191], v[38:41]
	v_mfma_f32_16x16x32_bf16 v[34:37], v[158:161], v[188:191], v[34:37]
	v_mfma_f32_16x16x32_bf16 v[22:25], v[150:153], v[196:199], v[22:25]
	v_mfma_f32_16x16x32_bf16 v[18:21], v[158:161], v[196:199], v[18:21]
	s_barrier
; #define PG8_STAGE(bufoff, gbase, voff) do { _Pragma("unroll") for (int _i = 0; _i < 2; ++_i) \
;         __builtin_amdgcn_global_load_lds((const unsigned*)((const char*)(gbase) + (voff)[_i]), (LAS unsigned*)(lds + (bufoff) + ldsw + _i * 8192), 16, 0, 0); } while (0)
; #define PG8_LDA(dst, b, h) do { _Pragma("unroll") for (int m = 0; m < 4; ++m) _Pragma("unroll") for (int k = 0; k < 2; ++k) dst[m][k] = *(const LAS bf16x8*)(lds + PG8_SA(b, h) + aoff + m * 2048 + k * 1024); } while (0)
; #define PG8_LDB(dst, b, h) do { _Pragma("unroll") for (int n = 0; n < 2; ++n) _Pragma("unroll") for (int k = 0; k < 2; ++k) dst[n][k] = *(const LAS bf16x8*)(lds + PG8_SB(b, h) + boff + n * 2048 + k * 1024); } while (0)
; #define PG8_WAIT_V(n) asm volatile("s_waitcnt vmcnt(" #n ")" ::: "memory")
; #define PG8_WAIT_L(n) asm volatile("s_waitcnt lgkmcnt(" #n ")" ::: "memory")
; #define PG8_BAR __builtin_amdgcn_s_barrier()
; #define PG8_SCHED __builtin_amdgcn_sched_barrier(0)
; template <class Epi>
; DI void gemm_phase(int wv, LAS unsigned char* lds, const GemmD g, const Epi& E) {
;     ...
;             PG8_LDB(B0, 0, 0); PG8_SCHED; PG8_LDA(At, 0, 0); PG8_STAGE(PG8_SA(1, 1), a1 + hstepA, voffA);
;             PG8_WAIT_L(8); PG8_BAR; PG8_WAIT_L(0); PG8_MMA(0, 0, At, B0); PG8_BAR; PG8_SCHED;
;             PG8_LDB(B1, 0, 1); PG8_STAGE(PG8_SB(0, 0), b2, voffB);
;             PG8_BAR; PG8_WAIT_L(0); PG8_MMA(0, 1, At, B1); PG8_BAR;
;             PG8_LDA(At, 0, 1); PG8_STAGE(PG8_SA(0, 0), a2, voffA);
;             PG8_BAR; PG8_WAIT_L(0); PG8_MMA(1, 0, At, B0); PG8_BAR; PG8_SCHED;
;             PG8_STAGE(PG8_SB(0, 1), b2 + hstepB, voffB);
;             PG8_WAIT_V(6); PG8_BAR; PG8_MMA(1, 1, At, B1); PG8_BAR;
;             PG8_LDB(B0, 1, 0); PG8_SCHED; PG8_LDA(At, 1, 0); PG8_STAGE(PG8_SA(0, 1), a2 + hstepA, voffA);
;             PG8_WAIT_L(8); PG8_BAR; PG8_WAIT_L(0); PG8_MMA(0, 0, At, B0); PG8_BAR; PG8_SCHED;
;             PG8_LDB(B1, 1, 1); PG8_STAGE(PG8_SB(1, 0), b3, voffB);
;             PG8_BAR; PG8_WAIT_L(0); PG8_MMA(0, 1, At, B1); PG8_BAR;
;             PG8_LDA(At, 1, 1); PG8_STAGE(PG8_SA(1, 0), a3, voffA);
;             PG8_BAR; PG8_WAIT_L(0); PG8_MMA(1, 0, At, B0); PG8_BAR; PG8_SCHED;
;             PG8_STAGE(PG8_SB(1, 1), b3 + hstepB, voffB);
;             PG8_WAIT_V(6); PG8_BAR; PG8_MMA(1, 1, At, B1); PG8_BAR;
	s_add_u32 s34, s34, s56
	s_addc_u32 s35, s35, 0
	s_add_i32 s2, s2, s84
	v_lshl_add_u64 v[224:225], s[34:35], 0, v[0:1]
	s_mov_b32 m0, s2
	v_lshl_add_u64 v[226:227], s[34:35], 0, v[134:135]
	global_load_lds_dwordx4 v[224:225], off
	s_add_i32 m0, s2, 0x2000
	s_nop 0
	global_load_lds_dwordx4 v[226:227], off
	s_waitcnt vmcnt(6)
	s_barrier
	v_mfma_f32_16x16x32_bf16 v[46:49], v[200:203], v[162:165], 0
	v_mfma_f32_16x16x32_bf16 v[42:45], v[208:211], v[162:165], 0
	v_mfma_f32_16x16x32_bf16 v[30:33], v[200:203], v[176:179], 0
	v_mfma_f32_16x16x32_bf16 v[26:29], v[208:211], v[176:179], 0
	v_mfma_f32_16x16x32_bf16 v[14:17], v[200:203], v[184:187], 0
	v_mfma_f32_16x16x32_bf16 v[10:13], v[208:211], v[184:187], 0
	v_mfma_f32_16x16x32_bf16 v[6:9], v[200:203], v[192:195], 0
	v_mfma_f32_16x16x32_bf16 v[2:5], v[208:211], v[192:195], 0
	v_mfma_f32_16x16x32_bf16 v[46:49], v[204:207], v[168:171], v[46:49]
	v_mfma_f32_16x16x32_bf16 v[42:45], v[212:215], v[168:171], v[42:45]
	v_mfma_f32_16x16x32_bf16 v[30:33], v[204:207], v[180:183], v[30:33]
	v_mfma_f32_16x16x32_bf16 v[26:29], v[212:215], v[180:183], v[26:29]
	v_mfma_f32_16x16x32_bf16 v[14:17], v[204:207], v[188:191], v[14:17]
	v_mfma_f32_16x16x32_bf16 v[10:13], v[212:215], v[188:191], v[10:13]
	v_mfma_f32_16x16x32_bf16 v[6:9], v[204:207], v[196:199], v[6:9]
	v_mfma_f32_16x16x32_bf16 v[2:5], v[212:215], v[196:199], v[2:5]
	s_add_i32 s2, 0, 0x18000
	v_add_u32_e32 v145, s2, v141
	s_barrier
	ds_read_b128 v[146:149], v145
	ds_read_b128 v[150:153], v145 offset:1024
	ds_read_b128 v[154:157], v145 offset:2048
	ds_read_b128 v[158:161], v145 offset:3072
	s_add_u32 s30, s30, s56
	s_addc_u32 s31, s31, 0
	s_mov_b32 m0, s74
	v_lshl_add_u64 v[200:201], s[30:31], 0, v[130:131]
	ds_read_b128 v[162:165], v144 offset:32768
	ds_read_b128 v[168:171], v144 offset:33792
	ds_read_b128 v[176:179], v144 offset:34816
	ds_read_b128 v[180:183], v144 offset:35840
	ds_read_b128 v[184:187], v144 offset:36864
	ds_read_b128 v[188:191], v144 offset:37888
	ds_read_b128 v[192:195], v144 offset:38912
	ds_read_b128 v[196:199], v144 offset:39936
	global_load_lds_dwordx4 v[200:201], off
	v_lshl_add_u64 v[200:201], s[30:31], 0, v[132:133]
	s_mov_b32 m0, s41
	s_nop 0
	global_load_lds_dwordx4 v[200:201], off
	s_waitcnt lgkmcnt(8)
	s_barrier
	s_waitcnt lgkmcnt(0)
	v_mfma_f32_16x16x32_bf16 v[126:129], v[146:149], v[162:165], v[126:129]
	v_mfma_f32_16x16x32_bf16 v[122:125], v[154:157], v[162:165], v[122:125]
	v_mfma_f32_16x16x32_bf16 v[118:121], v[146:149], v[176:179], v[118:121]
	v_mfma_f32_16x16x32_bf16 v[114:117], v[154:157], v[176:179], v[114:117]
	v_mfma_f32_16x16x32_bf16 v[102:105], v[146:149], v[184:187], v[102:105]
	v_mfma_f32_16x16x32_bf16 v[98:101], v[154:157], v[184:187], v[98:101]
	v_mfma_f32_16x16x32_bf16 v[86:89], v[146:149], v[192:195], v[86:89]
	v_mfma_f32_16x16x32_bf16 v[82:85], v[154:157], v[192:195], v[82:85]
	v_mfma_f32_16x16x32_bf16 v[126:129], v[150:153], v[168:171], v[126:129]
	v_mfma_f32_16x16x32_bf16 v[122:125], v[158:161], v[168:171], v[122:125]
	v_mfma_f32_16x16x32_bf16 v[118:121], v[150:153], v[180:183], v[118:121]
	v_mfma_f32_16x16x32_bf16 v[114:117], v[158:161], v[180:183], v[114:117]
	v_mfma_f32_16x16x32_bf16 v[102:105], v[150:153], v[188:191], v[102:105]
	v_mfma_f32_16x16x32_bf16 v[98:101], v[158:161], v[188:191], v[98:101]
	v_mfma_f32_16x16x32_bf16 v[86:89], v[150:153], v[196:199], v[86:89]
	v_mfma_f32_16x16x32_bf16 v[82:85], v[158:161], v[196:199], v[82:85]
	s_barrier
	s_add_i32 s3, 0, 0x1c000
	s_add_i32 s2, s2, s84
	v_add_u32_e32 v145, s3, v141
	v_lshl_add_u64 v[216:217], v[216:217], 0, s[58:59]
	s_mov_b32 m0, s2
	ds_read_b128 v[200:203], v145
	ds_read_b128 v[204:207], v145 offset:1024
	ds_read_b128 v[208:211], v145 offset:2048
	ds_read_b128 v[212:215], v145 offset:3072
	global_load_lds_dwordx4 v[216:217], off
	v_lshl_add_u64 v[216:217], v[218:219], 0, s[58:59]
	s_add_i32 m0, s2, 0x2000
	s_nop 0
	global_load_lds_dwordx4 v[216:217], off
	s_barrier
	s_waitcnt lgkmcnt(0)
	v_mfma_f32_16x16x32_bf16 v[110:113], v[200:203], v[162:165], v[110:113]
	v_mfma_f32_16x16x32_bf16 v[106:109], v[208:211], v[162:165], v[106:109]
	v_mfma_f32_16x16x32_bf16 v[94:97], v[200:203], v[176:179], v[94:97]
	v_mfma_f32_16x16x32_bf16 v[90:93], v[208:211], v[176:179], v[90:93]
	v_mfma_f32_16x16x32_bf16 v[78:81], v[200:203], v[184:187], v[78:81]
	v_mfma_f32_16x16x32_bf16 v[74:77], v[208:211], v[184:187], v[74:77]
	v_mfma_f32_16x16x32_bf16 v[70:73], v[200:203], v[192:195], v[70:73]
	v_mfma_f32_16x16x32_bf16 v[66:69], v[208:211], v[192:195], v[66:69]
	v_mfma_f32_16x16x32_bf16 v[110:113], v[204:207], v[168:171], v[110:113]
	v_mfma_f32_16x16x32_bf16 v[106:109], v[212:215], v[168:171], v[106:109]
	v_mfma_f32_16x16x32_bf16 v[94:97], v[204:207], v[180:183], v[94:97]
	v_mfma_f32_16x16x32_bf16 v[90:93], v[212:215], v[180:183], v[90:93]
	v_mfma_f32_16x16x32_bf16 v[78:81], v[204:207], v[188:191], v[78:81]
	v_mfma_f32_16x16x32_bf16 v[74:77], v[212:215], v[188:191], v[74:77]
	v_mfma_f32_16x16x32_bf16 v[70:73], v[204:207], v[196:199], v[70:73]
	v_mfma_f32_16x16x32_bf16 v[66:69], v[212:215], v[196:199], v[66:69]
	s_mov_b32 m0, s13
	v_lshl_add_u64 v[216:217], v[220:221], 0, s[58:59]
	s_barrier
	ds_read_b128 v[162:165], v144 offset:49152
	ds_read_b128 v[168:171], v144 offset:50176
	ds_read_b128 v[176:179], v144 offset:51200
	ds_read_b128 v[180:183], v144 offset:52224
	ds_read_b128 v[184:187], v144 offset:53248
	ds_read_b128 v[188:191], v144 offset:54272
	ds_read_b128 v[192:195], v144 offset:55296
	ds_read_b128 v[196:199], v144 offset:56320
	global_load_lds_dwordx4 v[216:217], off
	v_lshl_add_u64 v[216:217], v[222:223], 0, s[58:59]
	s_mov_b32 m0, s16
	s_nop 0
	global_load_lds_dwordx4 v[216:217], off
	s_barrier
; #define PG8_STAGE(bufoff, gbase, voff) do { _Pragma("unroll") for (int _i = 0; _i < 2; ++_i) \
;         __builtin_amdgcn_global_load_lds((const unsigned*)((const char*)(gbase) + (voff)[_i]), (LAS unsigned*)(lds + (bufoff) + ldsw + _i * 8192), 16, 0, 0); } while (0)
; #define PG8_LDA(dst, b, h) do { _Pragma("unroll") for (int m = 0; m < 4; ++m) _Pragma("unroll") for (int k = 0; k < 2; ++k) dst[m][k] = *(const LAS bf16x8*)(lds + PG8_SA(b, h) + aoff + m * 2048 + k * 1024); } while (0)
; #define PG8_WAIT_V(n) asm volatile("s_waitcnt vmcnt(" #n ")" ::: "memory")
; #define PG8_WAIT_L(n) asm volatile("s_waitcnt lgkmcnt(" #n ")" ::: "memory")
; #define PG8_BAR __builtin_amdgcn_s_barrier()
; template <class Epi>
; DI void gemm_phase(int wv, LAS unsigned char* lds, const GemmD g, const Epi& E) {
;     ...
;         for (int t = 0; t < nt; t += 2) {
;             const bool last = (t == nt - 2);
;             const char* a1 = cA + (size_t)(t + 1) * kstep;
;             const char* a2 = last ? nA : cA + (size_t)(t + 2) * kstep; const char* b2 = last ? nB : cB + (size_t)(t + 2) * kstep;
;             const char* a3 = a2 + kstep; const char* b3 = b2 + kstep;
;             PG8_LDB(B0, 0, 0); PG8_SCHED; PG8_LDA(At, 0, 0); PG8_STAGE(PG8_SA(1, 1), a1 + hstepA, voffA);
;             PG8_WAIT_L(8); PG8_BAR; PG8_WAIT_L(0); PG8_MMA(0, 0, At, B0); PG8_BAR; PG8_SCHED;
;             PG8_LDB(B1, 0, 1); PG8_STAGE(PG8_SB(0, 0), b2, voffB);
;             PG8_BAR; PG8_WAIT_L(0); PG8_MMA(0, 1, At, B1); PG8_BAR;
;             PG8_LDA(At, 0, 1); PG8_STAGE(PG8_SA(0, 0), a2, voffA);
;             PG8_BAR; PG8_WAIT_L(0); PG8_MMA(1, 0, At, B0); PG8_BAR; PG8_SCHED;
;             PG8_STAGE(PG8_SB(0, 1), b2 + hstepB, voffB);
;             PG8_WAIT_V(6); PG8_BAR; PG8_MMA(1, 1, At, B1); PG8_BAR;
;             PG8_LDB(B0, 1, 0); PG8_SCHED; PG8_LDA(At, 1, 0); PG8_STAGE(PG8_SA(0, 1), a2 + hstepA, voffA);
;             PG8_WAIT_L(8); PG8_BAR; PG8_WAIT_L(0); PG8_MMA(0, 0, At, B0); PG8_BAR; PG8_SCHED;
;             PG8_LDB(B1, 1, 1); PG8_STAGE(PG8_SB(1, 0), b3, voffB);
;             PG8_BAR; PG8_WAIT_L(0); PG8_MMA(0, 1, At, B1); PG8_BAR;
;             PG8_LDA(At, 1, 1); PG8_STAGE(PG8_SA(1, 0), a3, voffA);
;             PG8_BAR; PG8_WAIT_L(0); PG8_MMA(1, 0, At, B0); PG8_BAR; PG8_SCHED;
;             PG8_STAGE(PG8_SB(1, 1), b3 + hstepB, voffB);
;             PG8_WAIT_V(6); PG8_BAR; PG8_MMA(1, 1, At, B1); PG8_BAR;
	s_waitcnt lgkmcnt(0)
	v_mfma_f32_16x16x32_bf16 v[62:65], v[146:149], v[162:165], v[62:65]
	v_mfma_f32_16x16x32_bf16 v[58:61], v[154:157], v[162:165], v[58:61]
	v_mfma_f32_16x16x32_bf16 v[54:57], v[146:149], v[176:179], v[54:57]
	v_mfma_f32_16x16x32_bf16 v[50:53], v[154:157], v[176:179], v[50:53]
	v_mfma_f32_16x16x32_bf16 v[38:41], v[146:149], v[184:187], v[38:41]
	v_mfma_f32_16x16x32_bf16 v[34:37], v[154:157], v[184:187], v[34:37]
	v_mfma_f32_16x16x32_bf16 v[22:25], v[146:149], v[192:195], v[22:25]
	v_mfma_f32_16x16x32_bf16 v[18:21], v[154:157], v[192:195], v[18:21]
	v_mfma_f32_16x16x32_bf16 v[62:65], v[150:153], v[168:171], v[62:65]
	v_mfma_f32_16x16x32_bf16 v[58:61], v[158:161], v[168:171], v[58:61]
	v_mfma_f32_16x16x32_bf16 v[54:57], v[150:153], v[180:183], v[54:57]
	v_mfma_f32_16x16x32_bf16 v[50:53], v[158:161], v[180:183], v[50:53]
	v_mfma_f32_16x16x32_bf16 v[38:41], v[150:153], v[188:191], v[38:41]
	v_mfma_f32_16x16x32_bf16 v[34:37], v[158:161], v[188:191], v[34:37]
	v_mfma_f32_16x16x32_bf16 v[22:25], v[150:153], v[196:199], v[22:25]
	v_mfma_f32_16x16x32_bf16 v[18:21], v[158:161], v[196:199], v[18:21]
	s_barrier
	s_add_i32 s2, s3, s84
	v_lshl_add_u64 v[146:147], v[224:225], 0, s[58:59]
	s_mov_b32 m0, s2
	s_nop 0
	global_load_lds_dwordx4 v[146:147], off
	v_lshl_add_u64 v[146:147], v[226:227], 0, s[58:59]
	s_add_i32 m0, s2, 0x2000
	s_nop 0
	global_load_lds_dwordx4 v[146:147], off
	s_waitcnt vmcnt(6)
	s_barrier
	v_mfma_f32_16x16x32_bf16 v[46:49], v[200:203], v[162:165], v[46:49]
	v_mfma_f32_16x16x32_bf16 v[42:45], v[208:211], v[162:165], v[42:45]
	v_mfma_f32_16x16x32_bf16 v[30:33], v[200:203], v[176:179], v[30:33]
	v_mfma_f32_16x16x32_bf16 v[26:29], v[208:211], v[176:179], v[26:29]
	v_mfma_f32_16x16x32_bf16 v[14:17], v[200:203], v[184:187], v[14:17]
	v_mfma_f32_16x16x32_bf16 v[10:13], v[208:211], v[184:187], v[10:13]
	v_mfma_f32_16x16x32_bf16 v[6:9], v[200:203], v[192:195], v[6:9]
	v_mfma_f32_16x16x32_bf16 v[2:5], v[208:211], v[192:195], v[2:5]
	v_mfma_f32_16x16x32_bf16 v[46:49], v[204:207], v[168:171], v[46:49]
	v_mfma_f32_16x16x32_bf16 v[42:45], v[212:215], v[168:171], v[42:45]
	v_mfma_f32_16x16x32_bf16 v[30:33], v[204:207], v[180:183], v[30:33]
	v_mfma_f32_16x16x32_bf16 v[26:29], v[212:215], v[180:183], v[26:29]
	v_mfma_f32_16x16x32_bf16 v[14:17], v[204:207], v[188:191], v[14:17]
	v_mfma_f32_16x16x32_bf16 v[10:13], v[212:215], v[188:191], v[10:13]
	v_mfma_f32_16x16x32_bf16 v[6:9], v[204:207], v[196:199], v[6:9]
	v_mfma_f32_16x16x32_bf16 v[2:5], v[212:215], v[196:199], v[2:5]
	s_add_u32 s28, s28, 0x100
	s_addc_u32 s29, s29, 0
	s_add_u32 s37, s37, 0x100
	s_addc_u32 s18, s18, 0
	s_cmp_ge_u32 s95, s38
	s_mov_b32 s19, s95
	s_barrier
	s_cbranch_scc0 .LBB0_544
	s_branch .Lgemm_epi_c
	.p2align 6
.LBB0_544:
	s_add_i32 s95, s19, 2
	s_add_u32 s2, s28, 0x80
	s_addc_u32 s3, s29, 0
	s_add_i32 s94, 0, 0x10000
	v_add_u32_e32 v145, s94, v141
	ds_read_b128 v[146:149], v145
	ds_read_b128 v[150:153], v145 offset:1024
	ds_read_b128 v[154:157], v145 offset:2048
	ds_read_b128 v[158:161], v145 offset:3072
	s_cmp_eq_u32 s17, s19
	s_cselect_b32 s31, s23, s3
	s_cselect_b32 s30, s68, s2
	s_cselect_b32 s35, vcc_lo, s18
	s_cselect_b32 s34, vcc_hi, s37
	v_lshl_add_u64 v[200:201], s[28:29], 0, v[136:137]
	s_add_i32 m0, s86, 0xc000
	ds_read_b128 v[162:165], v144
	ds_read_b128 v[168:171], v144 offset:1024
	ds_read_b128 v[176:179], v144 offset:2048
	ds_read_b128 v[180:183], v144 offset:3072
	ds_read_b128 v[184:187], v144 offset:4096
	ds_read_b128 v[188:191], v144 offset:5120
	ds_read_b128 v[192:195], v144 offset:6144
	ds_read_b128 v[196:199], v144 offset:7168
	global_load_lds_dwordx4 v[200:201], off
	v_lshl_add_u64 v[200:201], s[28:29], 0, v[138:139]
	s_add_i32 m0, s86, 0xe000
	s_nop 0
	global_load_lds_dwordx4 v[200:201], off
	s_waitcnt lgkmcnt(8)
	s_barrier
	s_waitcnt lgkmcnt(0)
	v_mfma_f32_16x16x32_bf16 v[126:129], v[146:149], v[162:165], v[126:129]
	v_mfma_f32_16x16x32_bf16 v[122:125], v[154:157], v[162:165], v[122:125]
	v_mfma_f32_16x16x32_bf16 v[118:121], v[146:149], v[176:179], v[118:121]
	v_mfma_f32_16x16x32_bf16 v[114:117], v[154:157], v[176:179], v[114:117]
	v_mfma_f32_16x16x32_bf16 v[102:105], v[146:149], v[184:187], v[102:105]
	v_mfma_f32_16x16x32_bf16 v[98:101], v[154:157], v[184:187], v[98:101]
	v_mfma_f32_16x16x32_bf16 v[86:89], v[146:149], v[192:195], v[86:89]
	v_mfma_f32_16x16x32_bf16 v[82:85], v[154:157], v[192:195], v[82:85]
	v_mfma_f32_16x16x32_bf16 v[126:129], v[150:153], v[168:171], v[126:129]
	v_mfma_f32_16x16x32_bf16 v[122:125], v[158:161], v[168:171], v[122:125]
	v_mfma_f32_16x16x32_bf16 v[118:121], v[150:153], v[180:183], v[118:121]
	v_mfma_f32_16x16x32_bf16 v[114:117], v[158:161], v[180:183], v[114:117]
	v_mfma_f32_16x16x32_bf16 v[102:105], v[150:153], v[188:191], v[102:105]
	v_mfma_f32_16x16x32_bf16 v[98:101], v[158:161], v[188:191], v[98:101]
	v_mfma_f32_16x16x32_bf16 v[86:89], v[150:153], v[196:199], v[86:89]
	v_mfma_f32_16x16x32_bf16 v[82:85], v[158:161], v[196:199], v[82:85]
	s_barrier
	s_add_i32 s2, 0, 0x14000
	s_add_i32 s3, s94, s84
	v_add_u32_e32 v145, s2, v141
	v_lshl_add_u64 v[216:217], s[34:35], 0, v[0:1]
	s_mov_b32 m0, s3
	ds_read_b128 v[200:203], v145
	ds_read_b128 v[204:207], v145 offset:1024
	ds_read_b128 v[208:211], v145 offset:2048
	ds_read_b128 v[212:215], v145 offset:3072
	global_load_lds_dwordx4 v[216:217], off
	v_lshl_add_u64 v[218:219], s[34:35], 0, v[134:135]
	s_add_i32 m0, s3, 0x2000
	s_nop 0
	global_load_lds_dwordx4 v[218:219], off
	s_barrier
; #define PG8_STAGE(bufoff, gbase, voff) do { _Pragma("unroll") for (int _i = 0; _i < 2; ++_i) \
;         __builtin_amdgcn_global_load_lds((const unsigned*)((const char*)(gbase) + (voff)[_i]), (LAS unsigned*)(lds + (bufoff) + ldsw + _i * 8192), 16, 0, 0); } while (0)
; #define PG8_LDA(dst, b, h) do { _Pragma("unroll") for (int m = 0; m < 4; ++m) _Pragma("unroll") for (int k = 0; k < 2; ++k) dst[m][k] = *(const LAS bf16x8*)(lds + PG8_SA(b, h) + aoff + m * 2048 + k * 1024); } while (0)
; #define PG8_LDB(dst, b, h) do { _Pragma("unroll") for (int n = 0; n < 2; ++n) _Pragma("unroll") for (int k = 0; k < 2; ++k) dst[n][k] = *(const LAS bf16x8*)(lds + PG8_SB(b, h) + boff + n * 2048 + k * 1024); } while (0)
; #define PG8_WAIT_V(n) asm volatile("s_waitcnt vmcnt(" #n ")" ::: "memory")
; #define PG8_WAIT_L(n) asm volatile("s_waitcnt lgkmcnt(" #n ")" ::: "memory")
; #define PG8_BAR __builtin_amdgcn_s_barrier()
; #define PG8_SCHED __builtin_amdgcn_sched_barrier(0)
; template <class Epi>
; DI void gemm_phase(int wv, LAS unsigned char* lds, const GemmD g, const Epi& E) {
;     ...
;             PG8_LDB(B0, 0, 0); PG8_SCHED; PG8_LDA(At, 0, 0); PG8_STAGE(PG8_SA(1, 1), a1 + hstepA, voffA);
;             PG8_WAIT_L(8); PG8_BAR; PG8_WAIT_L(0); PG8_MMA(0, 0, At, B0); PG8_BAR; PG8_SCHED;
;             PG8_LDB(B1, 0, 1); PG8_STAGE(PG8_SB(0, 0), b2, voffB);
;             PG8_BAR; PG8_WAIT_L(0); PG8_MMA(0, 1, At, B1); PG8_BAR;
;             PG8_LDA(At, 0, 1); PG8_STAGE(PG8_SA(0, 0), a2, voffA);
;             PG8_BAR; PG8_WAIT_L(0); PG8_MMA(1, 0, At, B0); PG8_BAR; PG8_SCHED;
;             PG8_STAGE(PG8_SB(0, 1), b2 + hstepB, voffB);
;             PG8_WAIT_V(6); PG8_BAR; PG8_MMA(1, 1, At, B1); PG8_BAR;
;             PG8_LDB(B0, 1, 0); PG8_SCHED; PG8_LDA(At, 1, 0); PG8_STAGE(PG8_SA(0, 1), a2 + hstepA, voffA);
;             PG8_WAIT_L(8); PG8_BAR; PG8_WAIT_L(0); PG8_MMA(0, 0, At, B0); PG8_BAR; PG8_SCHED;
;             PG8_LDB(B1, 1, 1); PG8_STAGE(PG8_SB(1, 0), b3, voffB);
;             PG8_BAR; PG8_WAIT_L(0); PG8_MMA(0, 1, At, B1); PG8_BAR;
;             PG8_LDA(At, 1, 1); PG8_STAGE(PG8_SA(1, 0), a3, voffA);
;             PG8_BAR; PG8_WAIT_L(0); PG8_MMA(1, 0, At, B0); PG8_BAR; PG8_SCHED;
;             PG8_STAGE(PG8_SB(1, 1), b3 + hstepB, voffB);
;             PG8_WAIT_V(6); PG8_BAR; PG8_MMA(1, 1, At, B1); PG8_BAR;
	s_waitcnt lgkmcnt(0)
	v_mfma_f32_16x16x32_bf16 v[110:113], v[200:203], v[162:165], v[110:113]
	v_mfma_f32_16x16x32_bf16 v[106:109], v[208:211], v[162:165], v[106:109]
	v_mfma_f32_16x16x32_bf16 v[94:97], v[200:203], v[176:179], v[94:97]
	v_mfma_f32_16x16x32_bf16 v[90:93], v[208:211], v[176:179], v[90:93]
	v_mfma_f32_16x16x32_bf16 v[78:81], v[200:203], v[184:187], v[78:81]
	v_mfma_f32_16x16x32_bf16 v[74:77], v[208:211], v[184:187], v[74:77]
	v_mfma_f32_16x16x32_bf16 v[70:73], v[200:203], v[192:195], v[70:73]
	v_mfma_f32_16x16x32_bf16 v[66:69], v[208:211], v[192:195], v[66:69]
	v_mfma_f32_16x16x32_bf16 v[110:113], v[204:207], v[168:171], v[110:113]
	v_mfma_f32_16x16x32_bf16 v[106:109], v[212:215], v[168:171], v[106:109]
	v_mfma_f32_16x16x32_bf16 v[94:97], v[204:207], v[180:183], v[94:97]
	v_mfma_f32_16x16x32_bf16 v[90:93], v[212:215], v[180:183], v[90:93]
	v_mfma_f32_16x16x32_bf16 v[78:81], v[204:207], v[188:191], v[78:81]
	v_mfma_f32_16x16x32_bf16 v[74:77], v[212:215], v[188:191], v[74:77]
	v_mfma_f32_16x16x32_bf16 v[70:73], v[204:207], v[196:199], v[70:73]
	v_mfma_f32_16x16x32_bf16 v[66:69], v[212:215], v[196:199], v[66:69]
	s_mov_b32 m0, s86
	v_lshl_add_u64 v[220:221], s[30:31], 0, v[130:131]
	s_barrier
	ds_read_b128 v[162:165], v144 offset:16384
	ds_read_b128 v[168:171], v144 offset:17408
	ds_read_b128 v[176:179], v144 offset:18432
	ds_read_b128 v[180:183], v144 offset:19456
	ds_read_b128 v[184:187], v144 offset:20480
	ds_read_b128 v[188:191], v144 offset:21504
	ds_read_b128 v[192:195], v144 offset:22528
	ds_read_b128 v[196:199], v144 offset:23552
	global_load_lds_dwordx4 v[220:221], off
	v_lshl_add_u64 v[222:223], s[30:31], 0, v[132:133]
	s_mov_b32 m0, s87
	s_nop 0
	global_load_lds_dwordx4 v[222:223], off
	s_barrier
	s_waitcnt lgkmcnt(0)
	v_mfma_f32_16x16x32_bf16 v[62:65], v[146:149], v[162:165], v[62:65]
	v_mfma_f32_16x16x32_bf16 v[58:61], v[154:157], v[162:165], v[58:61]
	v_mfma_f32_16x16x32_bf16 v[54:57], v[146:149], v[176:179], v[54:57]
	v_mfma_f32_16x16x32_bf16 v[50:53], v[154:157], v[176:179], v[50:53]
	v_mfma_f32_16x16x32_bf16 v[38:41], v[146:149], v[184:187], v[38:41]
	v_mfma_f32_16x16x32_bf16 v[34:37], v[154:157], v[184:187], v[34:37]
	v_mfma_f32_16x16x32_bf16 v[22:25], v[146:149], v[192:195], v[22:25]
	v_mfma_f32_16x16x32_bf16 v[18:21], v[154:157], v[192:195], v[18:21]
	v_mfma_f32_16x16x32_bf16 v[62:65], v[150:153], v[168:171], v[62:65]
	v_mfma_f32_16x16x32_bf16 v[58:61], v[158:161], v[168:171], v[58:61]
	v_mfma_f32_16x16x32_bf16 v[54:57], v[150:153], v[180:183], v[54:57]
	v_mfma_f32_16x16x32_bf16 v[50:53], v[158:161], v[180:183], v[50:53]
	v_mfma_f32_16x16x32_bf16 v[38:41], v[150:153], v[188:191], v[38:41]
	v_mfma_f32_16x16x32_bf16 v[34:37], v[158:161], v[188:191], v[34:37]
	v_mfma_f32_16x16x32_bf16 v[22:25], v[150:153], v[196:199], v[22:25]
	v_mfma_f32_16x16x32_bf16 v[18:21], v[158:161], v[196:199], v[18:21]
	s_barrier
	s_add_u32 s34, s34, s56
	s_addc_u32 s35, s35, 0
	s_add_i32 s2, s2, s84
	v_lshl_add_u64 v[224:225], s[34:35], 0, v[0:1]
	s_mov_b32 m0, s2
	v_lshl_add_u64 v[226:227], s[34:35], 0, v[134:135]
	global_load_lds_dwordx4 v[224:225], off
	s_add_i32 m0, s2, 0x2000
	s_nop 0
	global_load_lds_dwordx4 v[226:227], off
	s_waitcnt vmcnt(6)
	s_barrier
	v_mfma_f32_16x16x32_bf16 v[46:49], v[200:203], v[162:165], v[46:49]
	v_mfma_f32_16x16x32_bf16 v[42:45], v[208:211], v[162:165], v[42:45]
	v_mfma_f32_16x16x32_bf16 v[30:33], v[200:203], v[176:179], v[30:33]
	v_mfma_f32_16x16x32_bf16 v[26:29], v[208:211], v[176:179], v[26:29]
	v_mfma_f32_16x16x32_bf16 v[14:17], v[200:203], v[184:187], v[14:17]
	v_mfma_f32_16x16x32_bf16 v[10:13], v[208:211], v[184:187], v[10:13]
	v_mfma_f32_16x16x32_bf16 v[6:9], v[200:203], v[192:195], v[6:9]
	v_mfma_f32_16x16x32_bf16 v[2:5], v[208:211], v[192:195], v[2:5]
	v_mfma_f32_16x16x32_bf16 v[46:49], v[204:207], v[168:171], v[46:49]
	v_mfma_f32_16x16x32_bf16 v[42:45], v[212:215], v[168:171], v[42:45]
	v_mfma_f32_16x16x32_bf16 v[30:33], v[204:207], v[180:183], v[30:33]
	v_mfma_f32_16x16x32_bf16 v[26:29], v[212:215], v[180:183], v[26:29]
	v_mfma_f32_16x16x32_bf16 v[14:17], v[204:207], v[188:191], v[14:17]
	v_mfma_f32_16x16x32_bf16 v[10:13], v[212:215], v[188:191], v[10:13]
	v_mfma_f32_16x16x32_bf16 v[6:9], v[204:207], v[196:199], v[6:9]
	v_mfma_f32_16x16x32_bf16 v[2:5], v[212:215], v[196:199], v[2:5]
	s_add_i32 s2, 0, 0x18000
	v_add_u32_e32 v145, s2, v141
	s_barrier
	ds_read_b128 v[146:149], v145
	ds_read_b128 v[150:153], v145 offset:1024
	ds_read_b128 v[154:157], v145 offset:2048
	ds_read_b128 v[158:161], v145 offset:3072
	s_add_u32 s30, s30, s56
	s_addc_u32 s31, s31, 0
	s_mov_b32 m0, s74
	v_lshl_add_u64 v[200:201], s[30:31], 0, v[130:131]
	ds_read_b128 v[162:165], v144 offset:32768
	ds_read_b128 v[168:171], v144 offset:33792
	ds_read_b128 v[176:179], v144 offset:34816
	ds_read_b128 v[180:183], v144 offset:35840
	ds_read_b128 v[184:187], v144 offset:36864
	ds_read_b128 v[188:191], v144 offset:37888
	ds_read_b128 v[192:195], v144 offset:38912
	ds_read_b128 v[196:199], v144 offset:39936
	global_load_lds_dwordx4 v[200:201], off
	v_lshl_add_u64 v[200:201], s[30:31], 0, v[132:133]
	s_mov_b32 m0, s41
	s_nop 0
	global_load_lds_dwordx4 v[200:201], off
	s_waitcnt lgkmcnt(8)
	s_barrier
; #define PG8_STAGE(bufoff, gbase, voff) do { _Pragma("unroll") for (int _i = 0; _i < 2; ++_i) \
;         __builtin_amdgcn_global_load_lds((const unsigned*)((const char*)(gbase) + (voff)[_i]), (LAS unsigned*)(lds + (bufoff) + ldsw + _i * 8192), 16, 0, 0); } while (0)
; #define PG8_LDA(dst, b, h) do { _Pragma("unroll") for (int m = 0; m < 4; ++m) _Pragma("unroll") for (int k = 0; k < 2; ++k) dst[m][k] = *(const LAS bf16x8*)(lds + PG8_SA(b, h) + aoff + m * 2048 + k * 1024); } while (0)
; #define PG8_LDB(dst, b, h) do { _Pragma("unroll") for (int n = 0; n < 2; ++n) _Pragma("unroll") for (int k = 0; k < 2; ++k) dst[n][k] = *(const LAS bf16x8*)(lds + PG8_SB(b, h) + boff + n * 2048 + k * 1024); } while (0)
; #define PG8_WAIT_V(n) asm volatile("s_waitcnt vmcnt(" #n ")" ::: "memory")
; #define PG8_WAIT_L(n) asm volatile("s_waitcnt lgkmcnt(" #n ")" ::: "memory")
; #define PG8_BAR __builtin_amdgcn_s_barrier()
; #define PG8_SCHED __builtin_amdgcn_sched_barrier(0)
; template <class Epi>
; DI void gemm_phase(int wv, LAS unsigned char* lds, const GemmD g, const Epi& E) {
;     ...
;             PG8_LDB(B0, 0, 0); PG8_SCHED; PG8_LDA(At, 0, 0); PG8_STAGE(PG8_SA(1, 1), a1 + hstepA, voffA);
;             PG8_WAIT_L(8); PG8_BAR; PG8_WAIT_L(0); PG8_MMA(0, 0, At, B0); PG8_BAR; PG8_SCHED;
;             PG8_LDB(B1, 0, 1); PG8_STAGE(PG8_SB(0, 0), b2, voffB);
;             PG8_BAR; PG8_WAIT_L(0); PG8_MMA(0, 1, At, B1); PG8_BAR;
;             PG8_LDA(At, 0, 1); PG8_STAGE(PG8_SA(0, 0), a2, voffA);
;             PG8_BAR; PG8_WAIT_L(0); PG8_MMA(1, 0, At, B0); PG8_BAR; PG8_SCHED;
;             PG8_STAGE(PG8_SB(0, 1), b2 + hstepB, voffB);
;             PG8_WAIT_V(6); PG8_BAR; PG8_MMA(1, 1, At, B1); PG8_BAR;
;             PG8_LDB(B0, 1, 0); PG8_SCHED; PG8_LDA(At, 1, 0); PG8_STAGE(PG8_SA(0, 1), a2 + hstepA, voffA);
;             PG8_WAIT_L(8); PG8_BAR; PG8_WAIT_L(0); PG8_MMA(0, 0, At, B0); PG8_BAR; PG8_SCHED;
;             PG8_LDB(B1, 1, 1); PG8_STAGE(PG8_SB(1, 0), b3, voffB);
;             PG8_BAR; PG8_WAIT_L(0); PG8_MMA(0, 1, At, B1); PG8_BAR;
;             PG8_LDA(At, 1, 1); PG8_STAGE(PG8_SA(1, 0), a3, voffA);
;             PG8_BAR; PG8_WAIT_L(0); PG8_MMA(1, 0, At, B0); PG8_BAR; PG8_SCHED;
;             PG8_STAGE(PG8_SB(1, 1), b3 + hstepB, voffB);
;             PG8_WAIT_V(6); PG8_BAR; PG8_MMA(1, 1, At, B1); PG8_BAR;
	s_waitcnt lgkmcnt(0)
	v_mfma_f32_16x16x32_bf16 v[126:129], v[146:149], v[162:165], v[126:129]
	v_mfma_f32_16x16x32_bf16 v[122:125], v[154:157], v[162:165], v[122:125]
	v_mfma_f32_16x16x32_bf16 v[118:121], v[146:149], v[176:179], v[118:121]
	v_mfma_f32_16x16x32_bf16 v[114:117], v[154:157], v[176:179], v[114:117]
	v_mfma_f32_16x16x32_bf16 v[102:105], v[146:149], v[184:187], v[102:105]
	v_mfma_f32_16x16x32_bf16 v[98:101], v[154:157], v[184:187], v[98:101]
	v_mfma_f32_16x16x32_bf16 v[86:89], v[146:149], v[192:195], v[86:89]
	v_mfma_f32_16x16x32_bf16 v[82:85], v[154:157], v[192:195], v[82:85]
	v_mfma_f32_16x16x32_bf16 v[126:129], v[150:153], v[168:171], v[126:129]
	v_mfma_f32_16x16x32_bf16 v[122:125], v[158:161], v[168:171], v[122:125]
	v_mfma_f32_16x16x32_bf16 v[118:121], v[150:153], v[180:183], v[118:121]
	v_mfma_f32_16x16x32_bf16 v[114:117], v[158:161], v[180:183], v[114:117]
	v_mfma_f32_16x16x32_bf16 v[102:105], v[150:153], v[188:191], v[102:105]
	v_mfma_f32_16x16x32_bf16 v[98:101], v[158:161], v[188:191], v[98:101]
	v_mfma_f32_16x16x32_bf16 v[86:89], v[150:153], v[196:199], v[86:89]
	v_mfma_f32_16x16x32_bf16 v[82:85], v[158:161], v[196:199], v[82:85]
	s_barrier
	s_add_i32 s3, 0, 0x1c000
	s_add_i32 s2, s2, s84
	v_add_u32_e32 v145, s3, v141
	v_lshl_add_u64 v[216:217], v[216:217], 0, s[58:59]
	s_mov_b32 m0, s2
	ds_read_b128 v[200:203], v145
	ds_read_b128 v[204:207], v145 offset:1024
	ds_read_b128 v[208:211], v145 offset:2048
	ds_read_b128 v[212:215], v145 offset:3072
	global_load_lds_dwordx4 v[216:217], off
	v_lshl_add_u64 v[216:217], v[218:219], 0, s[58:59]
	s_add_i32 m0, s2, 0x2000
	s_nop 0
	global_load_lds_dwordx4 v[216:217], off
	s_barrier
	s_waitcnt lgkmcnt(0)
	v_mfma_f32_16x16x32_bf16 v[110:113], v[200:203], v[162:165], v[110:113]
	v_mfma_f32_16x16x32_bf16 v[106:109], v[208:211], v[162:165], v[106:109]
	v_mfma_f32_16x16x32_bf16 v[94:97], v[200:203], v[176:179], v[94:97]
	v_mfma_f32_16x16x32_bf16 v[90:93], v[208:211], v[176:179], v[90:93]
	v_mfma_f32_16x16x32_bf16 v[78:81], v[200:203], v[184:187], v[78:81]
	v_mfma_f32_16x16x32_bf16 v[74:77], v[208:211], v[184:187], v[74:77]
	v_mfma_f32_16x16x32_bf16 v[70:73], v[200:203], v[192:195], v[70:73]
	v_mfma_f32_16x16x32_bf16 v[66:69], v[208:211], v[192:195], v[66:69]
	v_mfma_f32_16x16x32_bf16 v[110:113], v[204:207], v[168:171], v[110:113]
	v_mfma_f32_16x16x32_bf16 v[106:109], v[212:215], v[168:171], v[106:109]
	v_mfma_f32_16x16x32_bf16 v[94:97], v[204:207], v[180:183], v[94:97]
	v_mfma_f32_16x16x32_bf16 v[90:93], v[212:215], v[180:183], v[90:93]
	v_mfma_f32_16x16x32_bf16 v[78:81], v[204:207], v[188:191], v[78:81]
	v_mfma_f32_16x16x32_bf16 v[74:77], v[212:215], v[188:191], v[74:77]
	v_mfma_f32_16x16x32_bf16 v[70:73], v[204:207], v[196:199], v[70:73]
	v_mfma_f32_16x16x32_bf16 v[66:69], v[212:215], v[196:199], v[66:69]
	s_mov_b32 m0, s13
	v_lshl_add_u64 v[216:217], v[220:221], 0, s[58:59]
	s_barrier
	ds_read_b128 v[162:165], v144 offset:49152
	ds_read_b128 v[168:171], v144 offset:50176
	ds_read_b128 v[176:179], v144 offset:51200
	ds_read_b128 v[180:183], v144 offset:52224
	ds_read_b128 v[184:187], v144 offset:53248
	ds_read_b128 v[188:191], v144 offset:54272
	ds_read_b128 v[192:195], v144 offset:55296
	ds_read_b128 v[196:199], v144 offset:56320
	global_load_lds_dwordx4 v[216:217], off
	v_lshl_add_u64 v[216:217], v[222:223], 0, s[58:59]
	s_mov_b32 m0, s16
	s_nop 0
	global_load_lds_dwordx4 v[216:217], off
	s_barrier
	s_waitcnt lgkmcnt(0)
	v_mfma_f32_16x16x32_bf16 v[62:65], v[146:149], v[162:165], v[62:65]
	v_mfma_f32_16x16x32_bf16 v[58:61], v[154:157], v[162:165], v[58:61]
	v_mfma_f32_16x16x32_bf16 v[54:57], v[146:149], v[176:179], v[54:57]
	v_mfma_f32_16x16x32_bf16 v[50:53], v[154:157], v[176:179], v[50:53]
	v_mfma_f32_16x16x32_bf16 v[38:41], v[146:149], v[184:187], v[38:41]
	v_mfma_f32_16x16x32_bf16 v[34:37], v[154:157], v[184:187], v[34:37]
	v_mfma_f32_16x16x32_bf16 v[22:25], v[146:149], v[192:195], v[22:25]
	v_mfma_f32_16x16x32_bf16 v[18:21], v[154:157], v[192:195], v[18:21]
	v_mfma_f32_16x16x32_bf16 v[62:65], v[150:153], v[168:171], v[62:65]
	v_mfma_f32_16x16x32_bf16 v[58:61], v[158:161], v[168:171], v[58:61]
	v_mfma_f32_16x16x32_bf16 v[54:57], v[150:153], v[180:183], v[54:57]
	v_mfma_f32_16x16x32_bf16 v[50:53], v[158:161], v[180:183], v[50:53]
	v_mfma_f32_16x16x32_bf16 v[38:41], v[150:153], v[188:191], v[38:41]
	v_mfma_f32_16x16x32_bf16 v[34:37], v[158:161], v[188:191], v[34:37]
	v_mfma_f32_16x16x32_bf16 v[22:25], v[150:153], v[196:199], v[22:25]
	v_mfma_f32_16x16x32_bf16 v[18:21], v[158:161], v[196:199], v[18:21]
	s_barrier
	s_add_i32 s2, s3, s84
	v_lshl_add_u64 v[146:147], v[224:225], 0, s[58:59]
	s_mov_b32 m0, s2
	s_nop 0
	global_load_lds_dwordx4 v[146:147], off
	v_lshl_add_u64 v[146:147], v[226:227], 0, s[58:59]
	s_add_i32 m0, s2, 0x2000
	s_nop 0
	global_load_lds_dwordx4 v[146:147], off
	s_waitcnt vmcnt(6)
	s_barrier
	v_mfma_f32_16x16x32_bf16 v[46:49], v[200:203], v[162:165], v[46:49]
	v_mfma_f32_16x16x32_bf16 v[42:45], v[208:211], v[162:165], v[42:45]
	v_mfma_f32_16x16x32_bf16 v[30:33], v[200:203], v[176:179], v[30:33]
	v_mfma_f32_16x16x32_bf16 v[26:29], v[208:211], v[176:179], v[26:29]
	v_mfma_f32_16x16x32_bf16 v[14:17], v[200:203], v[184:187], v[14:17]
	v_mfma_f32_16x16x32_bf16 v[10:13], v[208:211], v[184:187], v[10:13]
	v_mfma_f32_16x16x32_bf16 v[6:9], v[200:203], v[192:195], v[6:9]
	v_mfma_f32_16x16x32_bf16 v[2:5], v[208:211], v[192:195], v[2:5]
	v_mfma_f32_16x16x32_bf16 v[46:49], v[204:207], v[168:171], v[46:49]
	v_mfma_f32_16x16x32_bf16 v[42:45], v[212:215], v[168:171], v[42:45]
	v_mfma_f32_16x16x32_bf16 v[30:33], v[204:207], v[180:183], v[30:33]
	v_mfma_f32_16x16x32_bf16 v[26:29], v[212:215], v[180:183], v[26:29]
	v_mfma_f32_16x16x32_bf16 v[14:17], v[204:207], v[188:191], v[14:17]
	v_mfma_f32_16x16x32_bf16 v[10:13], v[212:215], v[188:191], v[10:13]
	v_mfma_f32_16x16x32_bf16 v[6:9], v[204:207], v[196:199], v[6:9]
	v_mfma_f32_16x16x32_bf16 v[2:5], v[212:215], v[196:199], v[2:5]
	s_add_u32 s28, s28, 0x100
	s_addc_u32 s29, s29, 0
	s_add_u32 s37, s37, 0x100
	s_addc_u32 s18, s18, 0
	s_cmp_ge_u32 s95, s38
	s_mov_b32 s19, s95
	s_barrier
	s_cbranch_scc0 .LBB0_544
